# PEER u,v phases: expert ids and gates of each 8-token batch staged in LDS by LDS-DMA instead of broadcast vector loads
# speedup vs baseline: 1.0933x; 1.0179x over previous
; DI void gat_loadh(const unsigned char* base, int idlo, int idhi, int g8, unsigned lo16, u32x4 (&buf)[8]) {
;     const int ids = g8 < 8 ? idlo : idhi, e0 = (g8 & 7) * 8;
; #pragma unroll
;     for (int j = 0; j < 8; ++j) buf[j] = *(const u32x4*)(base + ((unsigned)__shfl(ids, e0 + j) * (unsigned)D + lo16));
; }
; DI void phase_peer_v(const Args& a, int layer, int ci) {
;     ...
;     int m = gw;
;     if (m < M) {
;         int idA = IDX[(size_t)m * 128 + lane], idB = IDX[(size_t)m * 128 + 64 + lane];
;         u32x4 cur[8];
;         gat_loadh(V, idA, idB, 0, lo16, cur);
; #pragma unroll 1
;         for (; m < M; m += NGW) {
;             const int mn = m + NGW < M ? m + NGW : m;
;             const int idAn = IDX[(size_t)mn * 128 + lane], idBn = IDX[(size_t)mn * 128 + 64 + lane];
;             const float ghA = GH[(size_t)m * 128 + lane], ghB = GH[(size_t)m * 128 + 64 + lane];
;             float acc[16];
; #pragma unroll
;             for (int i = 0; i < 16; ++i) acc[i] = 0.f;
; #pragma unroll 1
;             for (int g8 = 0; g8 < 16; ++g8) {
;                 u32x4 nxt[8];
;                 if (g8 < 15) gat_loadh(V, idA, idB, g8 + 1, lo16, nxt); else gat_loadh(V, idAn, idBn, 0, lo16, nxt);
.Lpv_entry:
	v_readlane_b32 s1, v252, 0
	v_readlane_b32 s19, v255, 12
	v_lshrrev_b32_e32 v5, 6, v185
	v_and_b32_e32 v6, 63, v185
	v_and_b32_e32 v7, 7, v6
	v_lshrrev_b32_e32 v6, 3, v6
	v_readfirstlane_b32 s44, v5
	v_lshlrev_b32_e32 v0, 4, v7
	v_lshlrev_b32_e32 v1, 9, v6
	v_lshlrev_b32_e32 v2, 13, v6
	v_lshl_or_b32 v2, v7, 6, v2
	s_lshr_b32 s45, s1, 3
	s_lshl_b32 s45, s45, 3
	s_add_u32 s45, s45, s44
	s_lshl_b32 s8, s45, 12
	s_and_b32 s9, s1, 7
	s_lshl_b32 s9, s9, 1
	s_lshl_b32 s46, s19, 25
	s_add_u32 s16, s98, 0x10000000
	s_addc_u32 s17, s99, 0
	s_add_u32 s16, s16, s46
	s_addc_u32 s17, s17, 0
	s_mov_b32 s0, 0
	s_lshl_b32 s1, s44, 14
	v_and_b32_e32 v5, 63, v185
	v_lshlrev_b32_e32 v238, 4, v5
	v_mov_b32_e32 v239, 0
	v_add_u32_e32 v240, s1, v1
	s_mov_b32 s19, 0
	s_and_b32 s45, s19, 15
	s_lshl_b32 s45, s45, 20
	s_add_u32 s45, s45, s8
	s_and_b32 s46, s19, 1
	s_lshl_b32 s46, s46, 12
	s_add_u32 s46, s46, s1
	s_add_u32 s100, s45, 0x6000000
	s_add_u32 s22, s98, s100
	s_addc_u32 s23, s99, 0
	v_lshl_add_u64 v[6:7], s[22:23], 0, v[238:239]
	s_mov_b32 m0, s46
	s_nop 0
	global_load_lds_dwordx4 v[6:7], off
	global_load_lds_dwordx4 v[6:7], off offset:1024
	global_load_lds_dwordx4 v[6:7], off offset:2048
	global_load_lds_dwordx4 v[6:7], off offset:3072
	s_add_u32 s100, s45, 0x7000000
	s_add_u32 s22, s98, s100
	s_addc_u32 s23, s99, 0
	v_lshl_add_u64 v[6:7], s[22:23], 0, v[238:239]
	s_add_u32 s46, s46, 0x2000
	s_mov_b32 m0, s46
	s_nop 0
	global_load_lds_dwordx4 v[6:7], off
	global_load_lds_dwordx4 v[6:7], off offset:1024
	global_load_lds_dwordx4 v[6:7], off offset:2048
	global_load_lds_dwordx4 v[6:7], off offset:3072
	s_lshr_b32 s46, s0, 7
	s_add_u32 s46, s46, s9
	s_lshl_b32 s46, s46, 21
	s_add_u32 s40, s16, s46
	s_addc_u32 s41, s17, 0
	v_mov_b64_e32 v[156:157], 0
	v_mov_b64_e32 v[158:159], 0
	v_mov_b64_e32 v[160:161], 0
	v_mov_b64_e32 v[162:163], 0
	v_mov_b64_e32 v[166:167], 0
	v_mov_b64_e32 v[168:169], 0
	v_mov_b64_e32 v[170:171], 0
	v_mov_b64_e32 v[172:173], 0
	s_waitcnt vmcnt(0)
	s_mov_b32 s44, 0
	s_bfe_u32 s45, s44, 0x10003
	s_lshl_b32 s45, s45, 12
	s_and_b32 s46, s44, 7
	s_lshl_b32 s46, s46, 6
	s_add_u32 s45, s45, s46
	v_add_u32_e32 v5, s45, v240
	ds_read_b128 v[72:75], v5
	ds_read_b128 v[76:79], v5 offset:16
	ds_read_b128 v[80:83], v5 offset:32
	ds_read_b128 v[84:87], v5 offset:48
	s_bfe_u32 s45, s44, 0x10003
	s_lshl_b32 s45, s45, 12
	s_and_b32 s46, s44, 7
	s_lshl_b32 s46, s46, 6
	s_add_u32 s45, s45, s46
	s_add_u32 s45, s45, 0x2000
	v_add_u32_e32 v5, s45, v240
	ds_read_b128 v[104:107], v5
	ds_read_b128 v[108:111], v5 offset:16
	ds_read_b128 v[112:115], v5 offset:32
	ds_read_b128 v[116:119], v5 offset:48
	s_mov_b32 s44, 1
	s_bfe_u32 s45, s44, 0x10003
	s_lshl_b32 s45, s45, 12
	s_and_b32 s46, s44, 7
	s_lshl_b32 s46, s46, 6
	s_add_u32 s45, s45, s46
	v_add_u32_e32 v5, s45, v240
	ds_read_b128 v[88:91], v5
	ds_read_b128 v[92:95], v5 offset:16
	ds_read_b128 v[96:99], v5 offset:32
	ds_read_b128 v[100:103], v5 offset:48
	s_waitcnt lgkmcnt(0)
	v_lshl_add_u32 v3, v72, 7, v0
	global_load_dwordx4 v[8:11], v3, s[40:41]
	v_lshl_add_u32 v4, v73, 7, v0
	global_load_dwordx4 v[12:15], v4, s[40:41]
	v_lshl_add_u32 v3, v74, 7, v0
	global_load_dwordx4 v[16:19], v3, s[40:41]
	v_lshl_add_u32 v4, v75, 7, v0
	global_load_dwordx4 v[20:23], v4, s[40:41]
	v_lshl_add_u32 v3, v76, 7, v0
	global_load_dwordx4 v[24:27], v3, s[40:41]
	v_lshl_add_u32 v4, v77, 7, v0
	global_load_dwordx4 v[28:31], v4, s[40:41]
	v_lshl_add_u32 v3, v78, 7, v0
	global_load_dwordx4 v[32:35], v3, s[40:41]
	v_lshl_add_u32 v4, v79, 7, v0
	global_load_dwordx4 v[36:39], v4, s[40:41]
	v_lshl_add_u32 v3, v80, 7, v0
	global_load_dwordx4 v[40:43], v3, s[40:41]
	v_lshl_add_u32 v4, v81, 7, v0
	global_load_dwordx4 v[44:47], v4, s[40:41]
	v_lshl_add_u32 v3, v82, 7, v0
	global_load_dwordx4 v[48:51], v3, s[40:41]
	v_lshl_add_u32 v4, v83, 7, v0
	global_load_dwordx4 v[52:55], v4, s[40:41]
	v_lshl_add_u32 v3, v84, 7, v0
	global_load_dwordx4 v[56:59], v3, s[40:41]
	v_lshl_add_u32 v4, v85, 7, v0
	global_load_dwordx4 v[60:63], v4, s[40:41]
	v_lshl_add_u32 v3, v86, 7, v0
	global_load_dwordx4 v[64:67], v3, s[40:41]
	v_lshl_add_u32 v4, v87, 7, v0
	global_load_dwordx4 v[68:71], v4, s[40:41]
.Lpv_loop:
	s_add_u32 s44, s0, 1
	s_min_u32 s44, s44, 0xff
	s_lshr_b32 s46, s44, 7
	s_add_u32 s46, s46, s9
	s_lshl_b32 s46, s46, 21
	s_add_u32 s40, s16, s46
	s_addc_u32 s41, s17, 0
	s_and_b32 s47, s0, 7
	s_cmp_eq_u32 s47, 0
	s_cbranch_scc0 .Lpv_b0_nodma
	s_lshr_b32 s19, s0, 3
	s_add_u32 s19, s19, 1
	s_min_u32 s19, s19, 31
	s_and_b32 s45, s19, 15
	s_lshl_b32 s45, s45, 20
	s_add_u32 s45, s45, s8
	s_and_b32 s46, s19, 1
	s_lshl_b32 s46, s46, 12
	s_add_u32 s46, s46, s1
	s_add_u32 s100, s45, 0x6000000
	s_add_u32 s22, s98, s100
	s_addc_u32 s23, s99, 0
	v_lshl_add_u64 v[6:7], s[22:23], 0, v[238:239]
	s_mov_b32 m0, s46
	s_nop 0
	global_load_lds_dwordx4 v[6:7], off
	global_load_lds_dwordx4 v[6:7], off offset:1024
	global_load_lds_dwordx4 v[6:7], off offset:2048
	global_load_lds_dwordx4 v[6:7], off offset:3072
	s_add_u32 s100, s45, 0x7000000
	s_add_u32 s22, s98, s100
	s_addc_u32 s23, s99, 0
	v_lshl_add_u64 v[6:7], s[22:23], 0, v[238:239]
	s_add_u32 s46, s46, 0x2000
	s_mov_b32 m0, s46
	s_nop 0
	global_load_lds_dwordx4 v[6:7], off
	global_load_lds_dwordx4 v[6:7], off offset:1024
	global_load_lds_dwordx4 v[6:7], off offset:2048
	global_load_lds_dwordx4 v[6:7], off offset:3072
.Lpv_b0_nodma:
	s_cmp_eq_u32 s47, 7
	s_cbranch_scc0 .Lpv_b0_noout
	s_bfe_u32 s45, s0, 0x40003
	s_lshl_b32 s45, s45, 24
	s_lshl_b32 s46, s8, 4
	s_add_u32 s45, s45, s46
	s_lshr_b32 s46, s0, 7
	s_add_u32 s46, s46, s9
	s_lshl_b32 s46, s46, 9
	s_add_u32 s45, s45, s46
	s_add_u32 s42, s96, s45
	s_addc_u32 s43, s97, 0
	global_load_dwordx4 v[216:219], v2, s[42:43]
	global_load_dwordx4 v[220:223], v2, s[42:43] offset:16
	global_load_dwordx4 v[224:227], v2, s[42:43] offset:32
	global_load_dwordx4 v[174:177], v2, s[42:43] offset:48
; #define FP8_LO(w) __builtin_amdgcn_cvt_pk_f32_fp8((int)(w), false)
; #define FP8_HI(w) __builtin_amdgcn_cvt_pk_f32_fp8((int)(w), true)
; DI void axpy16h(float (&acc)[16], float g, const u32x4 w) {
;     const f32x2 a0 = FP8_LO(w.x), a1 = FP8_HI(w.x), a2 = FP8_LO(w.y), a3 = FP8_HI(w.y), a4 = FP8_LO(w.z), a5 = FP8_HI(w.z), a6 = FP8_LO(w.w), a7 = FP8_HI(w.w);
;     acc[0] += g * a0.x; acc[1] += g * a0.y; acc[2] += g * a1.x; acc[3] += g * a1.y; acc[4] += g * a2.x; acc[5] += g * a2.y; acc[6] += g * a3.x; acc[7] += g * a3.y;
;     acc[8] += g * a4.x; acc[9] += g * a4.y; acc[10] += g * a5.x; acc[11] += g * a5.y; acc[12] += g * a6.x; acc[13] += g * a6.y; acc[14] += g * a7.x; acc[15] += g * a7.y;
; }
; DI void phase_peer_v(const Args& a, int layer, int ci) {
;     ...
; #pragma unroll 1
;             for (int g8 = 0; g8 < 16; ++g8) {
;                 u32x4 nxt[8];
;                 if (g8 < 15) gat_loadh(V, idA, idB, g8 + 1, lo16, nxt); else gat_loadh(V, idAn, idBn, 0, lo16, nxt);
;                 const float ghs = g8 < 8 ? ghA : ghB;
; #pragma unroll
;                 for (int j = 0; j < 8; ++j) { const float gv = __shfl(ghs, (g8 & 7) * 8 + j); axpy16h(acc, gv, cur[j]); if (j & 1) __builtin_amdgcn_sched_barrier(0); }
; #pragma unroll
;                 for (int j = 0; j < 8; ++j) cur[j] = nxt[j];
.Lpv_b0_noout:
	s_waitcnt lgkmcnt(0)
	s_bfe_u32 s45, s44, 0x10003
	s_lshl_b32 s45, s45, 12
	s_and_b32 s46, s44, 7
	s_lshl_b32 s46, s46, 6
	s_add_u32 s45, s45, s46
	s_add_u32 s45, s45, 0x2000
	v_add_u32_e32 v5, s45, v240
	ds_read_b128 v[140:143], v5
	ds_read_b128 v[144:147], v5 offset:16
	ds_read_b128 v[148:151], v5 offset:32
	ds_read_b128 v[152:155], v5 offset:48
	s_add_u32 s44, s0, 2
	s_min_u32 s44, s44, 0xff
	s_bfe_u32 s45, s44, 0x10003
	s_lshl_b32 s45, s45, 12
	s_and_b32 s46, s44, 7
	s_lshl_b32 s46, s46, 6
	s_add_u32 s45, s45, s46
	v_add_u32_e32 v5, s45, v240
	ds_read_b128 v[72:75], v5
	ds_read_b128 v[76:79], v5 offset:16
	ds_read_b128 v[80:83], v5 offset:32
	ds_read_b128 v[84:87], v5 offset:48
	s_waitcnt vmcnt(15)
	v_cvt_pk_f32_fp8_e32 v[120:121], v8
	v_cvt_pk_f32_fp8_sdwa v[122:123], v8 src0_sel:WORD_1
	v_cvt_pk_f32_fp8_e32 v[124:125], v9
	v_cvt_pk_f32_fp8_sdwa v[126:127], v9 src0_sel:WORD_1
	v_pk_fma_f32 v[156:157], v[120:121], v[104:105], v[156:157] op_sel_hi:[1,0,1]
	v_pk_fma_f32 v[158:159], v[122:123], v[104:105], v[158:159] op_sel_hi:[1,0,1]
	v_pk_fma_f32 v[160:161], v[124:125], v[104:105], v[160:161] op_sel_hi:[1,0,1]
	v_pk_fma_f32 v[162:163], v[126:127], v[104:105], v[162:163] op_sel_hi:[1,0,1]
	v_cvt_pk_f32_fp8_e32 v[120:121], v10
	v_cvt_pk_f32_fp8_sdwa v[122:123], v10 src0_sel:WORD_1
	v_cvt_pk_f32_fp8_e32 v[124:125], v11
	v_cvt_pk_f32_fp8_sdwa v[126:127], v11 src0_sel:WORD_1
	v_pk_fma_f32 v[166:167], v[120:121], v[104:105], v[166:167] op_sel_hi:[1,0,1]
	v_pk_fma_f32 v[168:169], v[122:123], v[104:105], v[168:169] op_sel_hi:[1,0,1]
	v_pk_fma_f32 v[170:171], v[124:125], v[104:105], v[170:171] op_sel_hi:[1,0,1]
	v_pk_fma_f32 v[172:173], v[126:127], v[104:105], v[172:173] op_sel_hi:[1,0,1]
	v_lshl_add_u32 v3, v88, 7, v0
	global_load_dwordx4 v[8:11], v3, s[40:41]
	s_waitcnt vmcnt(15)
	v_cvt_pk_f32_fp8_e32 v[120:121], v12
	v_cvt_pk_f32_fp8_sdwa v[122:123], v12 src0_sel:WORD_1
	v_cvt_pk_f32_fp8_e32 v[124:125], v13
	v_cvt_pk_f32_fp8_sdwa v[126:127], v13 src0_sel:WORD_1
	v_pk_fma_f32 v[156:157], v[120:121], v[104:105], v[156:157] op_sel:[0,1,0] op_sel_hi:[1,1,1]
	v_pk_fma_f32 v[158:159], v[122:123], v[104:105], v[158:159] op_sel:[0,1,0] op_sel_hi:[1,1,1]
	v_pk_fma_f32 v[160:161], v[124:125], v[104:105], v[160:161] op_sel:[0,1,0] op_sel_hi:[1,1,1]
	v_pk_fma_f32 v[162:163], v[126:127], v[104:105], v[162:163] op_sel:[0,1,0] op_sel_hi:[1,1,1]
	v_cvt_pk_f32_fp8_e32 v[120:121], v14
	v_cvt_pk_f32_fp8_sdwa v[122:123], v14 src0_sel:WORD_1
	v_cvt_pk_f32_fp8_e32 v[124:125], v15
	v_cvt_pk_f32_fp8_sdwa v[126:127], v15 src0_sel:WORD_1
	v_pk_fma_f32 v[166:167], v[120:121], v[104:105], v[166:167] op_sel:[0,1,0] op_sel_hi:[1,1,1]
	v_pk_fma_f32 v[168:169], v[122:123], v[104:105], v[168:169] op_sel:[0,1,0] op_sel_hi:[1,1,1]
	v_pk_fma_f32 v[170:171], v[124:125], v[104:105], v[170:171] op_sel:[0,1,0] op_sel_hi:[1,1,1]
	v_pk_fma_f32 v[172:173], v[126:127], v[104:105], v[172:173] op_sel:[0,1,0] op_sel_hi:[1,1,1]
	v_lshl_add_u32 v4, v89, 7, v0
	global_load_dwordx4 v[12:15], v4, s[40:41]
	s_waitcnt vmcnt(15)
	v_cvt_pk_f32_fp8_e32 v[120:121], v16
	v_cvt_pk_f32_fp8_sdwa v[122:123], v16 src0_sel:WORD_1
	v_cvt_pk_f32_fp8_e32 v[124:125], v17
	v_cvt_pk_f32_fp8_sdwa v[126:127], v17 src0_sel:WORD_1
	v_pk_fma_f32 v[156:157], v[120:121], v[106:107], v[156:157] op_sel_hi:[1,0,1]
	v_pk_fma_f32 v[158:159], v[122:123], v[106:107], v[158:159] op_sel_hi:[1,0,1]
	v_pk_fma_f32 v[160:161], v[124:125], v[106:107], v[160:161] op_sel_hi:[1,0,1]
	v_pk_fma_f32 v[162:163], v[126:127], v[106:107], v[162:163] op_sel_hi:[1,0,1]
	v_cvt_pk_f32_fp8_e32 v[120:121], v18
	v_cvt_pk_f32_fp8_sdwa v[122:123], v18 src0_sel:WORD_1
	v_cvt_pk_f32_fp8_e32 v[124:125], v19
	v_cvt_pk_f32_fp8_sdwa v[126:127], v19 src0_sel:WORD_1
	v_pk_fma_f32 v[166:167], v[120:121], v[106:107], v[166:167] op_sel_hi:[1,0,1]
	v_pk_fma_f32 v[168:169], v[122:123], v[106:107], v[168:169] op_sel_hi:[1,0,1]
	v_pk_fma_f32 v[170:171], v[124:125], v[106:107], v[170:171] op_sel_hi:[1,0,1]
	v_pk_fma_f32 v[172:173], v[126:127], v[106:107], v[172:173] op_sel_hi:[1,0,1]
	v_lshl_add_u32 v3, v90, 7, v0
	global_load_dwordx4 v[16:19], v3, s[40:41]
	s_waitcnt vmcnt(15)
	v_cvt_pk_f32_fp8_e32 v[120:121], v20
	v_cvt_pk_f32_fp8_sdwa v[122:123], v20 src0_sel:WORD_1
	v_cvt_pk_f32_fp8_e32 v[124:125], v21
	v_cvt_pk_f32_fp8_sdwa v[126:127], v21 src0_sel:WORD_1
	v_pk_fma_f32 v[156:157], v[120:121], v[106:107], v[156:157] op_sel:[0,1,0] op_sel_hi:[1,1,1]
	v_pk_fma_f32 v[158:159], v[122:123], v[106:107], v[158:159] op_sel:[0,1,0] op_sel_hi:[1,1,1]
	v_pk_fma_f32 v[160:161], v[124:125], v[106:107], v[160:161] op_sel:[0,1,0] op_sel_hi:[1,1,1]
	v_pk_fma_f32 v[162:163], v[126:127], v[106:107], v[162:163] op_sel:[0,1,0] op_sel_hi:[1,1,1]
	v_cvt_pk_f32_fp8_e32 v[120:121], v22
	v_cvt_pk_f32_fp8_sdwa v[122:123], v22 src0_sel:WORD_1
	v_cvt_pk_f32_fp8_e32 v[124:125], v23
	v_cvt_pk_f32_fp8_sdwa v[126:127], v23 src0_sel:WORD_1
	v_pk_fma_f32 v[166:167], v[120:121], v[106:107], v[166:167] op_sel:[0,1,0] op_sel_hi:[1,1,1]
	v_pk_fma_f32 v[168:169], v[122:123], v[106:107], v[168:169] op_sel:[0,1,0] op_sel_hi:[1,1,1]
	v_pk_fma_f32 v[170:171], v[124:125], v[106:107], v[170:171] op_sel:[0,1,0] op_sel_hi:[1,1,1]
	v_pk_fma_f32 v[172:173], v[126:127], v[106:107], v[172:173] op_sel:[0,1,0] op_sel_hi:[1,1,1]
	v_lshl_add_u32 v4, v91, 7, v0
	global_load_dwordx4 v[20:23], v4, s[40:41]
	s_waitcnt vmcnt(15)
; #define FP8_LO(w) __builtin_amdgcn_cvt_pk_f32_fp8((int)(w), false)
; #define FP8_HI(w) __builtin_amdgcn_cvt_pk_f32_fp8((int)(w), true)
; DI void axpy16h(float (&acc)[16], float g, const u32x4 w) {
;     const f32x2 a0 = FP8_LO(w.x), a1 = FP8_HI(w.x), a2 = FP8_LO(w.y), a3 = FP8_HI(w.y), a4 = FP8_LO(w.z), a5 = FP8_HI(w.z), a6 = FP8_LO(w.w), a7 = FP8_HI(w.w);
;     acc[0] += g * a0.x; acc[1] += g * a0.y; acc[2] += g * a1.x; acc[3] += g * a1.y; acc[4] += g * a2.x; acc[5] += g * a2.y; acc[6] += g * a3.x; acc[7] += g * a3.y;
;     acc[8] += g * a4.x; acc[9] += g * a4.y; acc[10] += g * a5.x; acc[11] += g * a5.y; acc[12] += g * a6.x; acc[13] += g * a6.y; acc[14] += g * a7.x; acc[15] += g * a7.y;
; }
; DI void phase_peer_v(const Args& a, int layer, int ci) {
;     ...
;             for (int g8 = 0; g8 < 16; ++g8) {
;                 u32x4 nxt[8];
;                 if (g8 < 15) gat_loadh(V, idA, idB, g8 + 1, lo16, nxt); else gat_loadh(V, idAn, idBn, 0, lo16, nxt);
;                 const float ghs = g8 < 8 ? ghA : ghB;
; #pragma unroll
;                 for (int j = 0; j < 8; ++j) { const float gv = __shfl(ghs, (g8 & 7) * 8 + j); axpy16h(acc, gv, cur[j]); if (j & 1) __builtin_amdgcn_sched_barrier(0); }
	v_cvt_pk_f32_fp8_e32 v[120:121], v24
	v_cvt_pk_f32_fp8_sdwa v[122:123], v24 src0_sel:WORD_1
	v_cvt_pk_f32_fp8_e32 v[124:125], v25
	v_cvt_pk_f32_fp8_sdwa v[126:127], v25 src0_sel:WORD_1
	v_pk_fma_f32 v[156:157], v[120:121], v[108:109], v[156:157] op_sel_hi:[1,0,1]
	v_pk_fma_f32 v[158:159], v[122:123], v[108:109], v[158:159] op_sel_hi:[1,0,1]
	v_pk_fma_f32 v[160:161], v[124:125], v[108:109], v[160:161] op_sel_hi:[1,0,1]
	v_pk_fma_f32 v[162:163], v[126:127], v[108:109], v[162:163] op_sel_hi:[1,0,1]
	v_cvt_pk_f32_fp8_e32 v[120:121], v26
	v_cvt_pk_f32_fp8_sdwa v[122:123], v26 src0_sel:WORD_1
	v_cvt_pk_f32_fp8_e32 v[124:125], v27
	v_cvt_pk_f32_fp8_sdwa v[126:127], v27 src0_sel:WORD_1
	v_pk_fma_f32 v[166:167], v[120:121], v[108:109], v[166:167] op_sel_hi:[1,0,1]
	v_pk_fma_f32 v[168:169], v[122:123], v[108:109], v[168:169] op_sel_hi:[1,0,1]
	v_pk_fma_f32 v[170:171], v[124:125], v[108:109], v[170:171] op_sel_hi:[1,0,1]
	v_pk_fma_f32 v[172:173], v[126:127], v[108:109], v[172:173] op_sel_hi:[1,0,1]
	v_lshl_add_u32 v3, v92, 7, v0
	global_load_dwordx4 v[24:27], v3, s[40:41]
	s_waitcnt vmcnt(15)
	v_cvt_pk_f32_fp8_e32 v[120:121], v28
	v_cvt_pk_f32_fp8_sdwa v[122:123], v28 src0_sel:WORD_1
	v_cvt_pk_f32_fp8_e32 v[124:125], v29
	v_cvt_pk_f32_fp8_sdwa v[126:127], v29 src0_sel:WORD_1
	v_pk_fma_f32 v[156:157], v[120:121], v[108:109], v[156:157] op_sel:[0,1,0] op_sel_hi:[1,1,1]
	v_pk_fma_f32 v[158:159], v[122:123], v[108:109], v[158:159] op_sel:[0,1,0] op_sel_hi:[1,1,1]
	v_pk_fma_f32 v[160:161], v[124:125], v[108:109], v[160:161] op_sel:[0,1,0] op_sel_hi:[1,1,1]
	v_pk_fma_f32 v[162:163], v[126:127], v[108:109], v[162:163] op_sel:[0,1,0] op_sel_hi:[1,1,1]
	v_cvt_pk_f32_fp8_e32 v[120:121], v30
	v_cvt_pk_f32_fp8_sdwa v[122:123], v30 src0_sel:WORD_1
	v_cvt_pk_f32_fp8_e32 v[124:125], v31
	v_cvt_pk_f32_fp8_sdwa v[126:127], v31 src0_sel:WORD_1
	v_pk_fma_f32 v[166:167], v[120:121], v[108:109], v[166:167] op_sel:[0,1,0] op_sel_hi:[1,1,1]
	v_pk_fma_f32 v[168:169], v[122:123], v[108:109], v[168:169] op_sel:[0,1,0] op_sel_hi:[1,1,1]
	v_pk_fma_f32 v[170:171], v[124:125], v[108:109], v[170:171] op_sel:[0,1,0] op_sel_hi:[1,1,1]
	v_pk_fma_f32 v[172:173], v[126:127], v[108:109], v[172:173] op_sel:[0,1,0] op_sel_hi:[1,1,1]
	v_lshl_add_u32 v4, v93, 7, v0
	global_load_dwordx4 v[28:31], v4, s[40:41]
	s_waitcnt vmcnt(15)
	v_cvt_pk_f32_fp8_e32 v[120:121], v32
	v_cvt_pk_f32_fp8_sdwa v[122:123], v32 src0_sel:WORD_1
	v_cvt_pk_f32_fp8_e32 v[124:125], v33
	v_cvt_pk_f32_fp8_sdwa v[126:127], v33 src0_sel:WORD_1
	v_pk_fma_f32 v[156:157], v[120:121], v[110:111], v[156:157] op_sel_hi:[1,0,1]
	v_pk_fma_f32 v[158:159], v[122:123], v[110:111], v[158:159] op_sel_hi:[1,0,1]
	v_pk_fma_f32 v[160:161], v[124:125], v[110:111], v[160:161] op_sel_hi:[1,0,1]
	v_pk_fma_f32 v[162:163], v[126:127], v[110:111], v[162:163] op_sel_hi:[1,0,1]
	v_cvt_pk_f32_fp8_e32 v[120:121], v34
	v_cvt_pk_f32_fp8_sdwa v[122:123], v34 src0_sel:WORD_1
	v_cvt_pk_f32_fp8_e32 v[124:125], v35
	v_cvt_pk_f32_fp8_sdwa v[126:127], v35 src0_sel:WORD_1
	v_pk_fma_f32 v[166:167], v[120:121], v[110:111], v[166:167] op_sel_hi:[1,0,1]
	v_pk_fma_f32 v[168:169], v[122:123], v[110:111], v[168:169] op_sel_hi:[1,0,1]
	v_pk_fma_f32 v[170:171], v[124:125], v[110:111], v[170:171] op_sel_hi:[1,0,1]
	v_pk_fma_f32 v[172:173], v[126:127], v[110:111], v[172:173] op_sel_hi:[1,0,1]
	v_lshl_add_u32 v3, v94, 7, v0
	global_load_dwordx4 v[32:35], v3, s[40:41]
	s_waitcnt vmcnt(15)
	v_cvt_pk_f32_fp8_e32 v[120:121], v36
	v_cvt_pk_f32_fp8_sdwa v[122:123], v36 src0_sel:WORD_1
	v_cvt_pk_f32_fp8_e32 v[124:125], v37
	v_cvt_pk_f32_fp8_sdwa v[126:127], v37 src0_sel:WORD_1
	v_pk_fma_f32 v[156:157], v[120:121], v[110:111], v[156:157] op_sel:[0,1,0] op_sel_hi:[1,1,1]
	v_pk_fma_f32 v[158:159], v[122:123], v[110:111], v[158:159] op_sel:[0,1,0] op_sel_hi:[1,1,1]
	v_pk_fma_f32 v[160:161], v[124:125], v[110:111], v[160:161] op_sel:[0,1,0] op_sel_hi:[1,1,1]
	v_pk_fma_f32 v[162:163], v[126:127], v[110:111], v[162:163] op_sel:[0,1,0] op_sel_hi:[1,1,1]
	v_cvt_pk_f32_fp8_e32 v[120:121], v38
	v_cvt_pk_f32_fp8_sdwa v[122:123], v38 src0_sel:WORD_1
	v_cvt_pk_f32_fp8_e32 v[124:125], v39
	v_cvt_pk_f32_fp8_sdwa v[126:127], v39 src0_sel:WORD_1
	v_pk_fma_f32 v[166:167], v[120:121], v[110:111], v[166:167] op_sel:[0,1,0] op_sel_hi:[1,1,1]
	v_pk_fma_f32 v[168:169], v[122:123], v[110:111], v[168:169] op_sel:[0,1,0] op_sel_hi:[1,1,1]
	v_pk_fma_f32 v[170:171], v[124:125], v[110:111], v[170:171] op_sel:[0,1,0] op_sel_hi:[1,1,1]
	v_pk_fma_f32 v[172:173], v[126:127], v[110:111], v[172:173] op_sel:[0,1,0] op_sel_hi:[1,1,1]
	v_lshl_add_u32 v4, v95, 7, v0
	global_load_dwordx4 v[36:39], v4, s[40:41]
	s_waitcnt vmcnt(15)
	v_cvt_pk_f32_fp8_e32 v[120:121], v40
	v_cvt_pk_f32_fp8_sdwa v[122:123], v40 src0_sel:WORD_1
	v_cvt_pk_f32_fp8_e32 v[124:125], v41
	v_cvt_pk_f32_fp8_sdwa v[126:127], v41 src0_sel:WORD_1
	v_pk_fma_f32 v[156:157], v[120:121], v[112:113], v[156:157] op_sel_hi:[1,0,1]
	v_pk_fma_f32 v[158:159], v[122:123], v[112:113], v[158:159] op_sel_hi:[1,0,1]
	v_pk_fma_f32 v[160:161], v[124:125], v[112:113], v[160:161] op_sel_hi:[1,0,1]
	v_pk_fma_f32 v[162:163], v[126:127], v[112:113], v[162:163] op_sel_hi:[1,0,1]
	v_cvt_pk_f32_fp8_e32 v[120:121], v42
	v_cvt_pk_f32_fp8_sdwa v[122:123], v42 src0_sel:WORD_1
	v_cvt_pk_f32_fp8_e32 v[124:125], v43
	v_cvt_pk_f32_fp8_sdwa v[126:127], v43 src0_sel:WORD_1
	v_pk_fma_f32 v[166:167], v[120:121], v[112:113], v[166:167] op_sel_hi:[1,0,1]
	v_pk_fma_f32 v[168:169], v[122:123], v[112:113], v[168:169] op_sel_hi:[1,0,1]
	v_pk_fma_f32 v[170:171], v[124:125], v[112:113], v[170:171] op_sel_hi:[1,0,1]
	v_pk_fma_f32 v[172:173], v[126:127], v[112:113], v[172:173] op_sel_hi:[1,0,1]
	v_lshl_add_u32 v3, v96, 7, v0
	global_load_dwordx4 v[40:43], v3, s[40:41]
	s_waitcnt vmcnt(15)
; #define FP8_LO(w) __builtin_amdgcn_cvt_pk_f32_fp8((int)(w), false)
; #define FP8_HI(w) __builtin_amdgcn_cvt_pk_f32_fp8((int)(w), true)
; DI void axpy16h(float (&acc)[16], float g, const u32x4 w) {
;     const f32x2 a0 = FP8_LO(w.x), a1 = FP8_HI(w.x), a2 = FP8_LO(w.y), a3 = FP8_HI(w.y), a4 = FP8_LO(w.z), a5 = FP8_HI(w.z), a6 = FP8_LO(w.w), a7 = FP8_HI(w.w);
;     acc[0] += g * a0.x; acc[1] += g * a0.y; acc[2] += g * a1.x; acc[3] += g * a1.y; acc[4] += g * a2.x; acc[5] += g * a2.y; acc[6] += g * a3.x; acc[7] += g * a3.y;
;     acc[8] += g * a4.x; acc[9] += g * a4.y; acc[10] += g * a5.x; acc[11] += g * a5.y; acc[12] += g * a6.x; acc[13] += g * a6.y; acc[14] += g * a7.x; acc[15] += g * a7.y;
; }
; DI void phase_peer_v(const Args& a, int layer, int ci) {
;     ...
;             for (int g8 = 0; g8 < 16; ++g8) {
;                 u32x4 nxt[8];
;                 if (g8 < 15) gat_loadh(V, idA, idB, g8 + 1, lo16, nxt); else gat_loadh(V, idAn, idBn, 0, lo16, nxt);
;                 const float ghs = g8 < 8 ? ghA : ghB;
; #pragma unroll
;                 for (int j = 0; j < 8; ++j) { const float gv = __shfl(ghs, (g8 & 7) * 8 + j); axpy16h(acc, gv, cur[j]); if (j & 1) __builtin_amdgcn_sched_barrier(0); }
	v_cvt_pk_f32_fp8_e32 v[120:121], v44
	v_cvt_pk_f32_fp8_sdwa v[122:123], v44 src0_sel:WORD_1
	v_cvt_pk_f32_fp8_e32 v[124:125], v45
	v_cvt_pk_f32_fp8_sdwa v[126:127], v45 src0_sel:WORD_1
	v_pk_fma_f32 v[156:157], v[120:121], v[112:113], v[156:157] op_sel:[0,1,0] op_sel_hi:[1,1,1]
	v_pk_fma_f32 v[158:159], v[122:123], v[112:113], v[158:159] op_sel:[0,1,0] op_sel_hi:[1,1,1]
	v_pk_fma_f32 v[160:161], v[124:125], v[112:113], v[160:161] op_sel:[0,1,0] op_sel_hi:[1,1,1]
	v_pk_fma_f32 v[162:163], v[126:127], v[112:113], v[162:163] op_sel:[0,1,0] op_sel_hi:[1,1,1]
	v_cvt_pk_f32_fp8_e32 v[120:121], v46
	v_cvt_pk_f32_fp8_sdwa v[122:123], v46 src0_sel:WORD_1
	v_cvt_pk_f32_fp8_e32 v[124:125], v47
	v_cvt_pk_f32_fp8_sdwa v[126:127], v47 src0_sel:WORD_1
	v_pk_fma_f32 v[166:167], v[120:121], v[112:113], v[166:167] op_sel:[0,1,0] op_sel_hi:[1,1,1]
	v_pk_fma_f32 v[168:169], v[122:123], v[112:113], v[168:169] op_sel:[0,1,0] op_sel_hi:[1,1,1]
	v_pk_fma_f32 v[170:171], v[124:125], v[112:113], v[170:171] op_sel:[0,1,0] op_sel_hi:[1,1,1]
	v_pk_fma_f32 v[172:173], v[126:127], v[112:113], v[172:173] op_sel:[0,1,0] op_sel_hi:[1,1,1]
	v_lshl_add_u32 v4, v97, 7, v0
	global_load_dwordx4 v[44:47], v4, s[40:41]
	s_waitcnt vmcnt(15)
	v_cvt_pk_f32_fp8_e32 v[120:121], v48
	v_cvt_pk_f32_fp8_sdwa v[122:123], v48 src0_sel:WORD_1
	v_cvt_pk_f32_fp8_e32 v[124:125], v49
	v_cvt_pk_f32_fp8_sdwa v[126:127], v49 src0_sel:WORD_1
	v_pk_fma_f32 v[156:157], v[120:121], v[114:115], v[156:157] op_sel_hi:[1,0,1]
	v_pk_fma_f32 v[158:159], v[122:123], v[114:115], v[158:159] op_sel_hi:[1,0,1]
	v_pk_fma_f32 v[160:161], v[124:125], v[114:115], v[160:161] op_sel_hi:[1,0,1]
	v_pk_fma_f32 v[162:163], v[126:127], v[114:115], v[162:163] op_sel_hi:[1,0,1]
	v_cvt_pk_f32_fp8_e32 v[120:121], v50
	v_cvt_pk_f32_fp8_sdwa v[122:123], v50 src0_sel:WORD_1
	v_cvt_pk_f32_fp8_e32 v[124:125], v51
	v_cvt_pk_f32_fp8_sdwa v[126:127], v51 src0_sel:WORD_1
	v_pk_fma_f32 v[166:167], v[120:121], v[114:115], v[166:167] op_sel_hi:[1,0,1]
	v_pk_fma_f32 v[168:169], v[122:123], v[114:115], v[168:169] op_sel_hi:[1,0,1]
	v_pk_fma_f32 v[170:171], v[124:125], v[114:115], v[170:171] op_sel_hi:[1,0,1]
	v_pk_fma_f32 v[172:173], v[126:127], v[114:115], v[172:173] op_sel_hi:[1,0,1]
	v_lshl_add_u32 v3, v98, 7, v0
	global_load_dwordx4 v[48:51], v3, s[40:41]
	s_waitcnt vmcnt(15)
	v_cvt_pk_f32_fp8_e32 v[120:121], v52
	v_cvt_pk_f32_fp8_sdwa v[122:123], v52 src0_sel:WORD_1
	v_cvt_pk_f32_fp8_e32 v[124:125], v53
	v_cvt_pk_f32_fp8_sdwa v[126:127], v53 src0_sel:WORD_1
	v_pk_fma_f32 v[156:157], v[120:121], v[114:115], v[156:157] op_sel:[0,1,0] op_sel_hi:[1,1,1]
	v_pk_fma_f32 v[158:159], v[122:123], v[114:115], v[158:159] op_sel:[0,1,0] op_sel_hi:[1,1,1]
	v_pk_fma_f32 v[160:161], v[124:125], v[114:115], v[160:161] op_sel:[0,1,0] op_sel_hi:[1,1,1]
	v_pk_fma_f32 v[162:163], v[126:127], v[114:115], v[162:163] op_sel:[0,1,0] op_sel_hi:[1,1,1]
	v_cvt_pk_f32_fp8_e32 v[120:121], v54
	v_cvt_pk_f32_fp8_sdwa v[122:123], v54 src0_sel:WORD_1
	v_cvt_pk_f32_fp8_e32 v[124:125], v55
	v_cvt_pk_f32_fp8_sdwa v[126:127], v55 src0_sel:WORD_1
	v_pk_fma_f32 v[166:167], v[120:121], v[114:115], v[166:167] op_sel:[0,1,0] op_sel_hi:[1,1,1]
	v_pk_fma_f32 v[168:169], v[122:123], v[114:115], v[168:169] op_sel:[0,1,0] op_sel_hi:[1,1,1]
	v_pk_fma_f32 v[170:171], v[124:125], v[114:115], v[170:171] op_sel:[0,1,0] op_sel_hi:[1,1,1]
	v_pk_fma_f32 v[172:173], v[126:127], v[114:115], v[172:173] op_sel:[0,1,0] op_sel_hi:[1,1,1]
	v_lshl_add_u32 v4, v99, 7, v0
	global_load_dwordx4 v[52:55], v4, s[40:41]
	s_waitcnt vmcnt(15)
	v_cvt_pk_f32_fp8_e32 v[120:121], v56
	v_cvt_pk_f32_fp8_sdwa v[122:123], v56 src0_sel:WORD_1
	v_cvt_pk_f32_fp8_e32 v[124:125], v57
	v_cvt_pk_f32_fp8_sdwa v[126:127], v57 src0_sel:WORD_1
	v_pk_fma_f32 v[156:157], v[120:121], v[116:117], v[156:157] op_sel_hi:[1,0,1]
	v_pk_fma_f32 v[158:159], v[122:123], v[116:117], v[158:159] op_sel_hi:[1,0,1]
	v_pk_fma_f32 v[160:161], v[124:125], v[116:117], v[160:161] op_sel_hi:[1,0,1]
	v_pk_fma_f32 v[162:163], v[126:127], v[116:117], v[162:163] op_sel_hi:[1,0,1]
	v_cvt_pk_f32_fp8_e32 v[120:121], v58
	v_cvt_pk_f32_fp8_sdwa v[122:123], v58 src0_sel:WORD_1
	v_cvt_pk_f32_fp8_e32 v[124:125], v59
	v_cvt_pk_f32_fp8_sdwa v[126:127], v59 src0_sel:WORD_1
	v_pk_fma_f32 v[166:167], v[120:121], v[116:117], v[166:167] op_sel_hi:[1,0,1]
	v_pk_fma_f32 v[168:169], v[122:123], v[116:117], v[168:169] op_sel_hi:[1,0,1]
	v_pk_fma_f32 v[170:171], v[124:125], v[116:117], v[170:171] op_sel_hi:[1,0,1]
	v_pk_fma_f32 v[172:173], v[126:127], v[116:117], v[172:173] op_sel_hi:[1,0,1]
	v_lshl_add_u32 v3, v100, 7, v0
	global_load_dwordx4 v[56:59], v3, s[40:41]
	s_waitcnt vmcnt(15)
; DI void phase_peer_v(const Args& a, int layer, int ci) {
;     ...
;             for (int g8 = 0; g8 < 16; ++g8) {
;                 u32x4 nxt[8];
;                 if (g8 < 15) gat_loadh(V, idA, idB, g8 + 1, lo16, nxt); else gat_loadh(V, idAn, idBn, 0, lo16, nxt);
;                 const float ghs = g8 < 8 ? ghA : ghB;
; #pragma unroll
;                 for (int j = 0; j < 8; ++j) { const float gv = __shfl(ghs, (g8 & 7) * 8 + j); axpy16h(acc, gv, cur[j]); if (j & 1) __builtin_amdgcn_sched_barrier(0); }
; #pragma unroll
;                 for (int j = 0; j < 8; ++j) cur[j] = nxt[j];
;             }
;             idA = idAn; idB = idBn;
;             float* hrow = a.out + (size_t)m * D;
;             const int col = ci * 1024 + lane * 16;
;             float ss = 0.f;
; #pragma unroll
;             for (int q = 0; q < 4; ++q) { const f32x4 h = *(const f32x4*)(hrow + col + 4 * q);
;                 acc[4 * q] += h.x; acc[4 * q + 1] += h.y; acc[4 * q + 2] += h.z; acc[4 * q + 3] += h.w; }
;             if (ci == 0) {
; #pragma unroll
;                 for (int q = 0; q < 4; ++q) { f32x4 h; h.x = acc[4 * q]; h.y = acc[4 * q + 1]; h.z = acc[4 * q + 2]; h.w = acc[4 * q + 3]; *(f32x4*)(hrow + col + 4 * q) = h; }
	v_cvt_pk_f32_fp8_e32 v[120:121], v60
	v_cvt_pk_f32_fp8_sdwa v[122:123], v60 src0_sel:WORD_1
	v_cvt_pk_f32_fp8_e32 v[124:125], v61
	v_cvt_pk_f32_fp8_sdwa v[126:127], v61 src0_sel:WORD_1
	v_pk_fma_f32 v[156:157], v[120:121], v[116:117], v[156:157] op_sel:[0,1,0] op_sel_hi:[1,1,1]
	v_pk_fma_f32 v[158:159], v[122:123], v[116:117], v[158:159] op_sel:[0,1,0] op_sel_hi:[1,1,1]
	v_pk_fma_f32 v[160:161], v[124:125], v[116:117], v[160:161] op_sel:[0,1,0] op_sel_hi:[1,1,1]
	v_pk_fma_f32 v[162:163], v[126:127], v[116:117], v[162:163] op_sel:[0,1,0] op_sel_hi:[1,1,1]
	v_cvt_pk_f32_fp8_e32 v[120:121], v62
	v_cvt_pk_f32_fp8_sdwa v[122:123], v62 src0_sel:WORD_1
	v_cvt_pk_f32_fp8_e32 v[124:125], v63
	v_cvt_pk_f32_fp8_sdwa v[126:127], v63 src0_sel:WORD_1
	v_pk_fma_f32 v[166:167], v[120:121], v[116:117], v[166:167] op_sel:[0,1,0] op_sel_hi:[1,1,1]
	v_pk_fma_f32 v[168:169], v[122:123], v[116:117], v[168:169] op_sel:[0,1,0] op_sel_hi:[1,1,1]
	v_pk_fma_f32 v[170:171], v[124:125], v[116:117], v[170:171] op_sel:[0,1,0] op_sel_hi:[1,1,1]
	v_pk_fma_f32 v[172:173], v[126:127], v[116:117], v[172:173] op_sel:[0,1,0] op_sel_hi:[1,1,1]
	v_lshl_add_u32 v4, v101, 7, v0
	global_load_dwordx4 v[60:63], v4, s[40:41]
	s_waitcnt vmcnt(15)
	v_cvt_pk_f32_fp8_e32 v[120:121], v64
	v_cvt_pk_f32_fp8_sdwa v[122:123], v64 src0_sel:WORD_1
	v_cvt_pk_f32_fp8_e32 v[124:125], v65
	v_cvt_pk_f32_fp8_sdwa v[126:127], v65 src0_sel:WORD_1
	v_pk_fma_f32 v[156:157], v[120:121], v[118:119], v[156:157] op_sel_hi:[1,0,1]
	v_pk_fma_f32 v[158:159], v[122:123], v[118:119], v[158:159] op_sel_hi:[1,0,1]
	v_pk_fma_f32 v[160:161], v[124:125], v[118:119], v[160:161] op_sel_hi:[1,0,1]
	v_pk_fma_f32 v[162:163], v[126:127], v[118:119], v[162:163] op_sel_hi:[1,0,1]
	v_cvt_pk_f32_fp8_e32 v[120:121], v66
	v_cvt_pk_f32_fp8_sdwa v[122:123], v66 src0_sel:WORD_1
	v_cvt_pk_f32_fp8_e32 v[124:125], v67
	v_cvt_pk_f32_fp8_sdwa v[126:127], v67 src0_sel:WORD_1
	v_pk_fma_f32 v[166:167], v[120:121], v[118:119], v[166:167] op_sel_hi:[1,0,1]
	v_pk_fma_f32 v[168:169], v[122:123], v[118:119], v[168:169] op_sel_hi:[1,0,1]
	v_pk_fma_f32 v[170:171], v[124:125], v[118:119], v[170:171] op_sel_hi:[1,0,1]
	v_pk_fma_f32 v[172:173], v[126:127], v[118:119], v[172:173] op_sel_hi:[1,0,1]
	v_lshl_add_u32 v3, v102, 7, v0
	global_load_dwordx4 v[64:67], v3, s[40:41]
	s_waitcnt vmcnt(15)
	v_cvt_pk_f32_fp8_e32 v[120:121], v68
	v_cvt_pk_f32_fp8_sdwa v[122:123], v68 src0_sel:WORD_1
	v_cvt_pk_f32_fp8_e32 v[124:125], v69
	v_cvt_pk_f32_fp8_sdwa v[126:127], v69 src0_sel:WORD_1
	v_pk_fma_f32 v[156:157], v[120:121], v[118:119], v[156:157] op_sel:[0,1,0] op_sel_hi:[1,1,1]
	v_pk_fma_f32 v[158:159], v[122:123], v[118:119], v[158:159] op_sel:[0,1,0] op_sel_hi:[1,1,1]
	v_pk_fma_f32 v[160:161], v[124:125], v[118:119], v[160:161] op_sel:[0,1,0] op_sel_hi:[1,1,1]
	v_pk_fma_f32 v[162:163], v[126:127], v[118:119], v[162:163] op_sel:[0,1,0] op_sel_hi:[1,1,1]
	v_cvt_pk_f32_fp8_e32 v[120:121], v70
	v_cvt_pk_f32_fp8_sdwa v[122:123], v70 src0_sel:WORD_1
	v_cvt_pk_f32_fp8_e32 v[124:125], v71
	v_cvt_pk_f32_fp8_sdwa v[126:127], v71 src0_sel:WORD_1
	v_pk_fma_f32 v[166:167], v[120:121], v[118:119], v[166:167] op_sel:[0,1,0] op_sel_hi:[1,1,1]
	v_pk_fma_f32 v[168:169], v[122:123], v[118:119], v[168:169] op_sel:[0,1,0] op_sel_hi:[1,1,1]
	v_pk_fma_f32 v[170:171], v[124:125], v[118:119], v[170:171] op_sel:[0,1,0] op_sel_hi:[1,1,1]
	v_pk_fma_f32 v[172:173], v[126:127], v[118:119], v[172:173] op_sel:[0,1,0] op_sel_hi:[1,1,1]
	v_lshl_add_u32 v4, v103, 7, v0
	global_load_dwordx4 v[68:71], v4, s[40:41]
	s_cmp_eq_u32 s47, 7
	s_cbranch_scc0 .Lpv_b0_nost
	v_pk_add_f32 v[216:217], v[216:217], v[156:157]
	v_pk_add_f32 v[218:219], v[218:219], v[158:159]
	v_pk_add_f32 v[220:221], v[220:221], v[160:161]
	v_pk_add_f32 v[222:223], v[222:223], v[162:163]
	v_pk_add_f32 v[224:225], v[224:225], v[166:167]
	v_pk_add_f32 v[226:227], v[226:227], v[168:169]
	v_pk_add_f32 v[174:175], v[174:175], v[170:171]
	v_pk_add_f32 v[176:177], v[176:177], v[172:173]
	v_mov_b64_e32 v[156:157], 0
	v_mov_b64_e32 v[158:159], 0
	v_mov_b64_e32 v[160:161], 0
	v_mov_b64_e32 v[162:163], 0
	v_mov_b64_e32 v[166:167], 0
	v_mov_b64_e32 v[168:169], 0
	v_mov_b64_e32 v[170:171], 0
	v_mov_b64_e32 v[172:173], 0
	global_store_dwordx4 v2, v[216:219], s[42:43]
	global_store_dwordx4 v2, v[220:223], s[42:43] offset:16
	global_store_dwordx4 v2, v[224:227], s[42:43] offset:32
	global_store_dwordx4 v2, v[174:177], s[42:43] offset:48
.Lpv_b0_nost:
	s_add_u32 s0, s0, 1
	s_add_u32 s44, s0, 1
	s_min_u32 s44, s44, 0xff
	s_lshr_b32 s46, s44, 7
	s_add_u32 s46, s46, s9
	s_lshl_b32 s46, s46, 21
	s_add_u32 s40, s16, s46
	s_addc_u32 s41, s17, 0
	s_and_b32 s47, s0, 7
	s_cmp_eq_u32 s47, 0
	s_cbranch_scc0 .Lpv_b1_nodma
	s_lshr_b32 s19, s0, 3
	s_add_u32 s19, s19, 1
	s_min_u32 s19, s19, 31
	s_and_b32 s45, s19, 15
	s_lshl_b32 s45, s45, 20
	s_add_u32 s45, s45, s8
	s_and_b32 s46, s19, 1
	s_lshl_b32 s46, s46, 12
	s_add_u32 s46, s46, s1
	s_add_u32 s100, s45, 0x6000000
	s_add_u32 s22, s98, s100
	s_addc_u32 s23, s99, 0
	v_lshl_add_u64 v[6:7], s[22:23], 0, v[238:239]
	s_mov_b32 m0, s46
	s_nop 0
	global_load_lds_dwordx4 v[6:7], off
	global_load_lds_dwordx4 v[6:7], off offset:1024
	global_load_lds_dwordx4 v[6:7], off offset:2048
	global_load_lds_dwordx4 v[6:7], off offset:3072
	s_add_u32 s100, s45, 0x7000000
	s_add_u32 s22, s98, s100
	s_addc_u32 s23, s99, 0
	v_lshl_add_u64 v[6:7], s[22:23], 0, v[238:239]
	s_add_u32 s46, s46, 0x2000
	s_mov_b32 m0, s46
	s_nop 0
	global_load_lds_dwordx4 v[6:7], off
	global_load_lds_dwordx4 v[6:7], off offset:1024
	global_load_lds_dwordx4 v[6:7], off offset:2048
	global_load_lds_dwordx4 v[6:7], off offset:3072

; #define FP8_LO(w) __builtin_amdgcn_cvt_pk_f32_fp8((int)(w), false)
; #define FP8_HI(w) __builtin_amdgcn_cvt_pk_f32_fp8((int)(w), true)
; DI void axpy16h(float (&acc)[16], float g, const u32x4 w) {
;     const f32x2 a0 = FP8_LO(w.x), a1 = FP8_HI(w.x), a2 = FP8_LO(w.y), a3 = FP8_HI(w.y), a4 = FP8_LO(w.z), a5 = FP8_HI(w.z), a6 = FP8_LO(w.w), a7 = FP8_HI(w.w);
;     acc[0] += g * a0.x; acc[1] += g * a0.y; acc[2] += g * a1.x; acc[3] += g * a1.y; acc[4] += g * a2.x; acc[5] += g * a2.y; acc[6] += g * a3.x; acc[7] += g * a3.y;
;     acc[8] += g * a4.x; acc[9] += g * a4.y; acc[10] += g * a5.x; acc[11] += g * a5.y; acc[12] += g * a6.x; acc[13] += g * a6.y; acc[14] += g * a7.x; acc[15] += g * a7.y;
; }
; DI void phase_peer_v(const Args& a, int layer, int ci) {
;     ...
; #pragma unroll 1
;             for (int g8 = 0; g8 < 16; ++g8) {
;                 u32x4 nxt[8];
;                 if (g8 < 15) gat_loadh(V, idA, idB, g8 + 1, lo16, nxt); else gat_loadh(V, idAn, idBn, 0, lo16, nxt);
;                 const float ghs = g8 < 8 ? ghA : ghB;
; #pragma unroll
;                 for (int j = 0; j < 8; ++j) { const float gv = __shfl(ghs, (g8 & 7) * 8 + j); axpy16h(acc, gv, cur[j]); if (j & 1) __builtin_amdgcn_sched_barrier(0); }
; #pragma unroll
;                 for (int j = 0; j < 8; ++j) cur[j] = nxt[j];
.Lpv_b1_noout:
	s_waitcnt lgkmcnt(0)
	s_bfe_u32 s45, s44, 0x10003
	s_lshl_b32 s45, s45, 12
	s_and_b32 s46, s44, 7
	s_lshl_b32 s46, s46, 6
	s_add_u32 s45, s45, s46
	s_add_u32 s45, s45, 0x2000
	v_add_u32_e32 v5, s45, v240
	ds_read_b128 v[104:107], v5
	ds_read_b128 v[108:111], v5 offset:16
	ds_read_b128 v[112:115], v5 offset:32
	ds_read_b128 v[116:119], v5 offset:48
	s_add_u32 s44, s0, 2
	s_min_u32 s44, s44, 0xff
	s_bfe_u32 s45, s44, 0x10003
	s_lshl_b32 s45, s45, 12
	s_and_b32 s46, s44, 7
	s_lshl_b32 s46, s46, 6
	s_add_u32 s45, s45, s46
	v_add_u32_e32 v5, s45, v240
	ds_read_b128 v[88:91], v5
	ds_read_b128 v[92:95], v5 offset:16
	ds_read_b128 v[96:99], v5 offset:32
	ds_read_b128 v[100:103], v5 offset:48
	s_waitcnt vmcnt(15)
	v_cvt_pk_f32_fp8_e32 v[120:121], v8
	v_cvt_pk_f32_fp8_sdwa v[122:123], v8 src0_sel:WORD_1
	v_cvt_pk_f32_fp8_e32 v[124:125], v9
	v_cvt_pk_f32_fp8_sdwa v[126:127], v9 src0_sel:WORD_1
	v_pk_fma_f32 v[156:157], v[120:121], v[140:141], v[156:157] op_sel_hi:[1,0,1]
	v_pk_fma_f32 v[158:159], v[122:123], v[140:141], v[158:159] op_sel_hi:[1,0,1]
	v_pk_fma_f32 v[160:161], v[124:125], v[140:141], v[160:161] op_sel_hi:[1,0,1]
	v_pk_fma_f32 v[162:163], v[126:127], v[140:141], v[162:163] op_sel_hi:[1,0,1]
	v_cvt_pk_f32_fp8_e32 v[120:121], v10
	v_cvt_pk_f32_fp8_sdwa v[122:123], v10 src0_sel:WORD_1
	v_cvt_pk_f32_fp8_e32 v[124:125], v11
	v_cvt_pk_f32_fp8_sdwa v[126:127], v11 src0_sel:WORD_1
	v_pk_fma_f32 v[166:167], v[120:121], v[140:141], v[166:167] op_sel_hi:[1,0,1]
	v_pk_fma_f32 v[168:169], v[122:123], v[140:141], v[168:169] op_sel_hi:[1,0,1]
	v_pk_fma_f32 v[170:171], v[124:125], v[140:141], v[170:171] op_sel_hi:[1,0,1]
	v_pk_fma_f32 v[172:173], v[126:127], v[140:141], v[172:173] op_sel_hi:[1,0,1]
	v_lshl_add_u32 v3, v72, 7, v0
	global_load_dwordx4 v[8:11], v3, s[40:41]
	s_waitcnt vmcnt(15)
	v_cvt_pk_f32_fp8_e32 v[120:121], v12
	v_cvt_pk_f32_fp8_sdwa v[122:123], v12 src0_sel:WORD_1
	v_cvt_pk_f32_fp8_e32 v[124:125], v13
	v_cvt_pk_f32_fp8_sdwa v[126:127], v13 src0_sel:WORD_1
	v_pk_fma_f32 v[156:157], v[120:121], v[140:141], v[156:157] op_sel:[0,1,0] op_sel_hi:[1,1,1]
	v_pk_fma_f32 v[158:159], v[122:123], v[140:141], v[158:159] op_sel:[0,1,0] op_sel_hi:[1,1,1]
	v_pk_fma_f32 v[160:161], v[124:125], v[140:141], v[160:161] op_sel:[0,1,0] op_sel_hi:[1,1,1]
	v_pk_fma_f32 v[162:163], v[126:127], v[140:141], v[162:163] op_sel:[0,1,0] op_sel_hi:[1,1,1]
	v_cvt_pk_f32_fp8_e32 v[120:121], v14
	v_cvt_pk_f32_fp8_sdwa v[122:123], v14 src0_sel:WORD_1
	v_cvt_pk_f32_fp8_e32 v[124:125], v15
	v_cvt_pk_f32_fp8_sdwa v[126:127], v15 src0_sel:WORD_1
	v_pk_fma_f32 v[166:167], v[120:121], v[140:141], v[166:167] op_sel:[0,1,0] op_sel_hi:[1,1,1]
	v_pk_fma_f32 v[168:169], v[122:123], v[140:141], v[168:169] op_sel:[0,1,0] op_sel_hi:[1,1,1]
	v_pk_fma_f32 v[170:171], v[124:125], v[140:141], v[170:171] op_sel:[0,1,0] op_sel_hi:[1,1,1]
	v_pk_fma_f32 v[172:173], v[126:127], v[140:141], v[172:173] op_sel:[0,1,0] op_sel_hi:[1,1,1]
	v_lshl_add_u32 v4, v73, 7, v0
	global_load_dwordx4 v[12:15], v4, s[40:41]
	s_waitcnt vmcnt(15)
	v_cvt_pk_f32_fp8_e32 v[120:121], v16
	v_cvt_pk_f32_fp8_sdwa v[122:123], v16 src0_sel:WORD_1
	v_cvt_pk_f32_fp8_e32 v[124:125], v17
	v_cvt_pk_f32_fp8_sdwa v[126:127], v17 src0_sel:WORD_1
	v_pk_fma_f32 v[156:157], v[120:121], v[142:143], v[156:157] op_sel_hi:[1,0,1]
	v_pk_fma_f32 v[158:159], v[122:123], v[142:143], v[158:159] op_sel_hi:[1,0,1]
	v_pk_fma_f32 v[160:161], v[124:125], v[142:143], v[160:161] op_sel_hi:[1,0,1]
	v_pk_fma_f32 v[162:163], v[126:127], v[142:143], v[162:163] op_sel_hi:[1,0,1]
	v_cvt_pk_f32_fp8_e32 v[120:121], v18
	v_cvt_pk_f32_fp8_sdwa v[122:123], v18 src0_sel:WORD_1
	v_cvt_pk_f32_fp8_e32 v[124:125], v19
	v_cvt_pk_f32_fp8_sdwa v[126:127], v19 src0_sel:WORD_1
	v_pk_fma_f32 v[166:167], v[120:121], v[142:143], v[166:167] op_sel_hi:[1,0,1]
	v_pk_fma_f32 v[168:169], v[122:123], v[142:143], v[168:169] op_sel_hi:[1,0,1]
	v_pk_fma_f32 v[170:171], v[124:125], v[142:143], v[170:171] op_sel_hi:[1,0,1]
	v_pk_fma_f32 v[172:173], v[126:127], v[142:143], v[172:173] op_sel_hi:[1,0,1]
	v_lshl_add_u32 v3, v74, 7, v0
	global_load_dwordx4 v[16:19], v3, s[40:41]
	s_waitcnt vmcnt(15)
	v_cvt_pk_f32_fp8_e32 v[120:121], v20
	v_cvt_pk_f32_fp8_sdwa v[122:123], v20 src0_sel:WORD_1
	v_cvt_pk_f32_fp8_e32 v[124:125], v21
	v_cvt_pk_f32_fp8_sdwa v[126:127], v21 src0_sel:WORD_1
	v_pk_fma_f32 v[156:157], v[120:121], v[142:143], v[156:157] op_sel:[0,1,0] op_sel_hi:[1,1,1]
	v_pk_fma_f32 v[158:159], v[122:123], v[142:143], v[158:159] op_sel:[0,1,0] op_sel_hi:[1,1,1]
	v_pk_fma_f32 v[160:161], v[124:125], v[142:143], v[160:161] op_sel:[0,1,0] op_sel_hi:[1,1,1]
	v_pk_fma_f32 v[162:163], v[126:127], v[142:143], v[162:163] op_sel:[0,1,0] op_sel_hi:[1,1,1]
	v_cvt_pk_f32_fp8_e32 v[120:121], v22
	v_cvt_pk_f32_fp8_sdwa v[122:123], v22 src0_sel:WORD_1
	v_cvt_pk_f32_fp8_e32 v[124:125], v23
	v_cvt_pk_f32_fp8_sdwa v[126:127], v23 src0_sel:WORD_1
	v_pk_fma_f32 v[166:167], v[120:121], v[142:143], v[166:167] op_sel:[0,1,0] op_sel_hi:[1,1,1]
	v_pk_fma_f32 v[168:169], v[122:123], v[142:143], v[168:169] op_sel:[0,1,0] op_sel_hi:[1,1,1]
	v_pk_fma_f32 v[170:171], v[124:125], v[142:143], v[170:171] op_sel:[0,1,0] op_sel_hi:[1,1,1]
	v_pk_fma_f32 v[172:173], v[126:127], v[142:143], v[172:173] op_sel:[0,1,0] op_sel_hi:[1,1,1]
	v_lshl_add_u32 v4, v75, 7, v0
	global_load_dwordx4 v[20:23], v4, s[40:41]
	s_waitcnt vmcnt(15)
; #define FP8_LO(w) __builtin_amdgcn_cvt_pk_f32_fp8((int)(w), false)
; #define FP8_HI(w) __builtin_amdgcn_cvt_pk_f32_fp8((int)(w), true)
; DI void axpy16h(float (&acc)[16], float g, const u32x4 w) {
;     const f32x2 a0 = FP8_LO(w.x), a1 = FP8_HI(w.x), a2 = FP8_LO(w.y), a3 = FP8_HI(w.y), a4 = FP8_LO(w.z), a5 = FP8_HI(w.z), a6 = FP8_LO(w.w), a7 = FP8_HI(w.w);
;     acc[0] += g * a0.x; acc[1] += g * a0.y; acc[2] += g * a1.x; acc[3] += g * a1.y; acc[4] += g * a2.x; acc[5] += g * a2.y; acc[6] += g * a3.x; acc[7] += g * a3.y;
;     acc[8] += g * a4.x; acc[9] += g * a4.y; acc[10] += g * a5.x; acc[11] += g * a5.y; acc[12] += g * a6.x; acc[13] += g * a6.y; acc[14] += g * a7.x; acc[15] += g * a7.y;
; }
; DI void phase_peer_v(const Args& a, int layer, int ci) {
;     ...
;             for (int g8 = 0; g8 < 16; ++g8) {
;                 u32x4 nxt[8];
;                 if (g8 < 15) gat_loadh(V, idA, idB, g8 + 1, lo16, nxt); else gat_loadh(V, idAn, idBn, 0, lo16, nxt);
;                 const float ghs = g8 < 8 ? ghA : ghB;
; #pragma unroll
;                 for (int j = 0; j < 8; ++j) { const float gv = __shfl(ghs, (g8 & 7) * 8 + j); axpy16h(acc, gv, cur[j]); if (j & 1) __builtin_amdgcn_sched_barrier(0); }
	v_cvt_pk_f32_fp8_e32 v[120:121], v24
	v_cvt_pk_f32_fp8_sdwa v[122:123], v24 src0_sel:WORD_1
	v_cvt_pk_f32_fp8_e32 v[124:125], v25
	v_cvt_pk_f32_fp8_sdwa v[126:127], v25 src0_sel:WORD_1
	v_pk_fma_f32 v[156:157], v[120:121], v[144:145], v[156:157] op_sel_hi:[1,0,1]
	v_pk_fma_f32 v[158:159], v[122:123], v[144:145], v[158:159] op_sel_hi:[1,0,1]
	v_pk_fma_f32 v[160:161], v[124:125], v[144:145], v[160:161] op_sel_hi:[1,0,1]
	v_pk_fma_f32 v[162:163], v[126:127], v[144:145], v[162:163] op_sel_hi:[1,0,1]
	v_cvt_pk_f32_fp8_e32 v[120:121], v26
	v_cvt_pk_f32_fp8_sdwa v[122:123], v26 src0_sel:WORD_1
	v_cvt_pk_f32_fp8_e32 v[124:125], v27
	v_cvt_pk_f32_fp8_sdwa v[126:127], v27 src0_sel:WORD_1
	v_pk_fma_f32 v[166:167], v[120:121], v[144:145], v[166:167] op_sel_hi:[1,0,1]
	v_pk_fma_f32 v[168:169], v[122:123], v[144:145], v[168:169] op_sel_hi:[1,0,1]
	v_pk_fma_f32 v[170:171], v[124:125], v[144:145], v[170:171] op_sel_hi:[1,0,1]
	v_pk_fma_f32 v[172:173], v[126:127], v[144:145], v[172:173] op_sel_hi:[1,0,1]
	v_lshl_add_u32 v3, v76, 7, v0
	global_load_dwordx4 v[24:27], v3, s[40:41]
	s_waitcnt vmcnt(15)
	v_cvt_pk_f32_fp8_e32 v[120:121], v28
	v_cvt_pk_f32_fp8_sdwa v[122:123], v28 src0_sel:WORD_1
	v_cvt_pk_f32_fp8_e32 v[124:125], v29
	v_cvt_pk_f32_fp8_sdwa v[126:127], v29 src0_sel:WORD_1
	v_pk_fma_f32 v[156:157], v[120:121], v[144:145], v[156:157] op_sel:[0,1,0] op_sel_hi:[1,1,1]
	v_pk_fma_f32 v[158:159], v[122:123], v[144:145], v[158:159] op_sel:[0,1,0] op_sel_hi:[1,1,1]
	v_pk_fma_f32 v[160:161], v[124:125], v[144:145], v[160:161] op_sel:[0,1,0] op_sel_hi:[1,1,1]
	v_pk_fma_f32 v[162:163], v[126:127], v[144:145], v[162:163] op_sel:[0,1,0] op_sel_hi:[1,1,1]
	v_cvt_pk_f32_fp8_e32 v[120:121], v30
	v_cvt_pk_f32_fp8_sdwa v[122:123], v30 src0_sel:WORD_1
	v_cvt_pk_f32_fp8_e32 v[124:125], v31
	v_cvt_pk_f32_fp8_sdwa v[126:127], v31 src0_sel:WORD_1
	v_pk_fma_f32 v[166:167], v[120:121], v[144:145], v[166:167] op_sel:[0,1,0] op_sel_hi:[1,1,1]
	v_pk_fma_f32 v[168:169], v[122:123], v[144:145], v[168:169] op_sel:[0,1,0] op_sel_hi:[1,1,1]
	v_pk_fma_f32 v[170:171], v[124:125], v[144:145], v[170:171] op_sel:[0,1,0] op_sel_hi:[1,1,1]
	v_pk_fma_f32 v[172:173], v[126:127], v[144:145], v[172:173] op_sel:[0,1,0] op_sel_hi:[1,1,1]
	v_lshl_add_u32 v4, v77, 7, v0
	global_load_dwordx4 v[28:31], v4, s[40:41]
	s_waitcnt vmcnt(15)
	v_cvt_pk_f32_fp8_e32 v[120:121], v32
	v_cvt_pk_f32_fp8_sdwa v[122:123], v32 src0_sel:WORD_1
	v_cvt_pk_f32_fp8_e32 v[124:125], v33
	v_cvt_pk_f32_fp8_sdwa v[126:127], v33 src0_sel:WORD_1
	v_pk_fma_f32 v[156:157], v[120:121], v[146:147], v[156:157] op_sel_hi:[1,0,1]
	v_pk_fma_f32 v[158:159], v[122:123], v[146:147], v[158:159] op_sel_hi:[1,0,1]
	v_pk_fma_f32 v[160:161], v[124:125], v[146:147], v[160:161] op_sel_hi:[1,0,1]
	v_pk_fma_f32 v[162:163], v[126:127], v[146:147], v[162:163] op_sel_hi:[1,0,1]
	v_cvt_pk_f32_fp8_e32 v[120:121], v34
	v_cvt_pk_f32_fp8_sdwa v[122:123], v34 src0_sel:WORD_1
	v_cvt_pk_f32_fp8_e32 v[124:125], v35
	v_cvt_pk_f32_fp8_sdwa v[126:127], v35 src0_sel:WORD_1
	v_pk_fma_f32 v[166:167], v[120:121], v[146:147], v[166:167] op_sel_hi:[1,0,1]
	v_pk_fma_f32 v[168:169], v[122:123], v[146:147], v[168:169] op_sel_hi:[1,0,1]
	v_pk_fma_f32 v[170:171], v[124:125], v[146:147], v[170:171] op_sel_hi:[1,0,1]
	v_pk_fma_f32 v[172:173], v[126:127], v[146:147], v[172:173] op_sel_hi:[1,0,1]
	v_lshl_add_u32 v3, v78, 7, v0
	global_load_dwordx4 v[32:35], v3, s[40:41]
	s_waitcnt vmcnt(15)
	v_cvt_pk_f32_fp8_e32 v[120:121], v36
	v_cvt_pk_f32_fp8_sdwa v[122:123], v36 src0_sel:WORD_1
	v_cvt_pk_f32_fp8_e32 v[124:125], v37
	v_cvt_pk_f32_fp8_sdwa v[126:127], v37 src0_sel:WORD_1
	v_pk_fma_f32 v[156:157], v[120:121], v[146:147], v[156:157] op_sel:[0,1,0] op_sel_hi:[1,1,1]
	v_pk_fma_f32 v[158:159], v[122:123], v[146:147], v[158:159] op_sel:[0,1,0] op_sel_hi:[1,1,1]
	v_pk_fma_f32 v[160:161], v[124:125], v[146:147], v[160:161] op_sel:[0,1,0] op_sel_hi:[1,1,1]
	v_pk_fma_f32 v[162:163], v[126:127], v[146:147], v[162:163] op_sel:[0,1,0] op_sel_hi:[1,1,1]
	v_cvt_pk_f32_fp8_e32 v[120:121], v38
	v_cvt_pk_f32_fp8_sdwa v[122:123], v38 src0_sel:WORD_1
	v_cvt_pk_f32_fp8_e32 v[124:125], v39
	v_cvt_pk_f32_fp8_sdwa v[126:127], v39 src0_sel:WORD_1
	v_pk_fma_f32 v[166:167], v[120:121], v[146:147], v[166:167] op_sel:[0,1,0] op_sel_hi:[1,1,1]
	v_pk_fma_f32 v[168:169], v[122:123], v[146:147], v[168:169] op_sel:[0,1,0] op_sel_hi:[1,1,1]
	v_pk_fma_f32 v[170:171], v[124:125], v[146:147], v[170:171] op_sel:[0,1,0] op_sel_hi:[1,1,1]
	v_pk_fma_f32 v[172:173], v[126:127], v[146:147], v[172:173] op_sel:[0,1,0] op_sel_hi:[1,1,1]
	v_lshl_add_u32 v4, v79, 7, v0
	global_load_dwordx4 v[36:39], v4, s[40:41]
	s_waitcnt vmcnt(15)
	v_cvt_pk_f32_fp8_e32 v[120:121], v40
	v_cvt_pk_f32_fp8_sdwa v[122:123], v40 src0_sel:WORD_1
	v_cvt_pk_f32_fp8_e32 v[124:125], v41
	v_cvt_pk_f32_fp8_sdwa v[126:127], v41 src0_sel:WORD_1
	v_pk_fma_f32 v[156:157], v[120:121], v[148:149], v[156:157] op_sel_hi:[1,0,1]
	v_pk_fma_f32 v[158:159], v[122:123], v[148:149], v[158:159] op_sel_hi:[1,0,1]
	v_pk_fma_f32 v[160:161], v[124:125], v[148:149], v[160:161] op_sel_hi:[1,0,1]
	v_pk_fma_f32 v[162:163], v[126:127], v[148:149], v[162:163] op_sel_hi:[1,0,1]
	v_cvt_pk_f32_fp8_e32 v[120:121], v42
	v_cvt_pk_f32_fp8_sdwa v[122:123], v42 src0_sel:WORD_1
	v_cvt_pk_f32_fp8_e32 v[124:125], v43
	v_cvt_pk_f32_fp8_sdwa v[126:127], v43 src0_sel:WORD_1
	v_pk_fma_f32 v[166:167], v[120:121], v[148:149], v[166:167] op_sel_hi:[1,0,1]
	v_pk_fma_f32 v[168:169], v[122:123], v[148:149], v[168:169] op_sel_hi:[1,0,1]
	v_pk_fma_f32 v[170:171], v[124:125], v[148:149], v[170:171] op_sel_hi:[1,0,1]
	v_pk_fma_f32 v[172:173], v[126:127], v[148:149], v[172:173] op_sel_hi:[1,0,1]
	v_lshl_add_u32 v3, v80, 7, v0
	global_load_dwordx4 v[40:43], v3, s[40:41]
	s_waitcnt vmcnt(15)
; #define FP8_LO(w) __builtin_amdgcn_cvt_pk_f32_fp8((int)(w), false)
; #define FP8_HI(w) __builtin_amdgcn_cvt_pk_f32_fp8((int)(w), true)
; DI void axpy16h(float (&acc)[16], float g, const u32x4 w) {
;     const f32x2 a0 = FP8_LO(w.x), a1 = FP8_HI(w.x), a2 = FP8_LO(w.y), a3 = FP8_HI(w.y), a4 = FP8_LO(w.z), a5 = FP8_HI(w.z), a6 = FP8_LO(w.w), a7 = FP8_HI(w.w);
;     acc[0] += g * a0.x; acc[1] += g * a0.y; acc[2] += g * a1.x; acc[3] += g * a1.y; acc[4] += g * a2.x; acc[5] += g * a2.y; acc[6] += g * a3.x; acc[7] += g * a3.y;
;     acc[8] += g * a4.x; acc[9] += g * a4.y; acc[10] += g * a5.x; acc[11] += g * a5.y; acc[12] += g * a6.x; acc[13] += g * a6.y; acc[14] += g * a7.x; acc[15] += g * a7.y;
; }
; DI void phase_peer_v(const Args& a, int layer, int ci) {
;     ...
;             for (int g8 = 0; g8 < 16; ++g8) {
;                 u32x4 nxt[8];
;                 if (g8 < 15) gat_loadh(V, idA, idB, g8 + 1, lo16, nxt); else gat_loadh(V, idAn, idBn, 0, lo16, nxt);
;                 const float ghs = g8 < 8 ? ghA : ghB;
; #pragma unroll
;                 for (int j = 0; j < 8; ++j) { const float gv = __shfl(ghs, (g8 & 7) * 8 + j); axpy16h(acc, gv, cur[j]); if (j & 1) __builtin_amdgcn_sched_barrier(0); }
	v_cvt_pk_f32_fp8_e32 v[120:121], v44
	v_cvt_pk_f32_fp8_sdwa v[122:123], v44 src0_sel:WORD_1
	v_cvt_pk_f32_fp8_e32 v[124:125], v45
	v_cvt_pk_f32_fp8_sdwa v[126:127], v45 src0_sel:WORD_1
	v_pk_fma_f32 v[156:157], v[120:121], v[148:149], v[156:157] op_sel:[0,1,0] op_sel_hi:[1,1,1]
	v_pk_fma_f32 v[158:159], v[122:123], v[148:149], v[158:159] op_sel:[0,1,0] op_sel_hi:[1,1,1]
	v_pk_fma_f32 v[160:161], v[124:125], v[148:149], v[160:161] op_sel:[0,1,0] op_sel_hi:[1,1,1]
	v_pk_fma_f32 v[162:163], v[126:127], v[148:149], v[162:163] op_sel:[0,1,0] op_sel_hi:[1,1,1]
	v_cvt_pk_f32_fp8_e32 v[120:121], v46
	v_cvt_pk_f32_fp8_sdwa v[122:123], v46 src0_sel:WORD_1
	v_cvt_pk_f32_fp8_e32 v[124:125], v47
	v_cvt_pk_f32_fp8_sdwa v[126:127], v47 src0_sel:WORD_1
	v_pk_fma_f32 v[166:167], v[120:121], v[148:149], v[166:167] op_sel:[0,1,0] op_sel_hi:[1,1,1]
	v_pk_fma_f32 v[168:169], v[122:123], v[148:149], v[168:169] op_sel:[0,1,0] op_sel_hi:[1,1,1]
	v_pk_fma_f32 v[170:171], v[124:125], v[148:149], v[170:171] op_sel:[0,1,0] op_sel_hi:[1,1,1]
	v_pk_fma_f32 v[172:173], v[126:127], v[148:149], v[172:173] op_sel:[0,1,0] op_sel_hi:[1,1,1]
	v_lshl_add_u32 v4, v81, 7, v0
	global_load_dwordx4 v[44:47], v4, s[40:41]
	s_waitcnt vmcnt(15)
	v_cvt_pk_f32_fp8_e32 v[120:121], v48
	v_cvt_pk_f32_fp8_sdwa v[122:123], v48 src0_sel:WORD_1
	v_cvt_pk_f32_fp8_e32 v[124:125], v49
	v_cvt_pk_f32_fp8_sdwa v[126:127], v49 src0_sel:WORD_1
	v_pk_fma_f32 v[156:157], v[120:121], v[150:151], v[156:157] op_sel_hi:[1,0,1]
	v_pk_fma_f32 v[158:159], v[122:123], v[150:151], v[158:159] op_sel_hi:[1,0,1]
	v_pk_fma_f32 v[160:161], v[124:125], v[150:151], v[160:161] op_sel_hi:[1,0,1]
	v_pk_fma_f32 v[162:163], v[126:127], v[150:151], v[162:163] op_sel_hi:[1,0,1]
	v_cvt_pk_f32_fp8_e32 v[120:121], v50
	v_cvt_pk_f32_fp8_sdwa v[122:123], v50 src0_sel:WORD_1
	v_cvt_pk_f32_fp8_e32 v[124:125], v51
	v_cvt_pk_f32_fp8_sdwa v[126:127], v51 src0_sel:WORD_1
	v_pk_fma_f32 v[166:167], v[120:121], v[150:151], v[166:167] op_sel_hi:[1,0,1]
	v_pk_fma_f32 v[168:169], v[122:123], v[150:151], v[168:169] op_sel_hi:[1,0,1]
	v_pk_fma_f32 v[170:171], v[124:125], v[150:151], v[170:171] op_sel_hi:[1,0,1]
	v_pk_fma_f32 v[172:173], v[126:127], v[150:151], v[172:173] op_sel_hi:[1,0,1]
	v_lshl_add_u32 v3, v82, 7, v0
	global_load_dwordx4 v[48:51], v3, s[40:41]
	s_waitcnt vmcnt(15)
	v_cvt_pk_f32_fp8_e32 v[120:121], v52
	v_cvt_pk_f32_fp8_sdwa v[122:123], v52 src0_sel:WORD_1
	v_cvt_pk_f32_fp8_e32 v[124:125], v53
	v_cvt_pk_f32_fp8_sdwa v[126:127], v53 src0_sel:WORD_1
	v_pk_fma_f32 v[156:157], v[120:121], v[150:151], v[156:157] op_sel:[0,1,0] op_sel_hi:[1,1,1]
	v_pk_fma_f32 v[158:159], v[122:123], v[150:151], v[158:159] op_sel:[0,1,0] op_sel_hi:[1,1,1]
	v_pk_fma_f32 v[160:161], v[124:125], v[150:151], v[160:161] op_sel:[0,1,0] op_sel_hi:[1,1,1]
	v_pk_fma_f32 v[162:163], v[126:127], v[150:151], v[162:163] op_sel:[0,1,0] op_sel_hi:[1,1,1]
	v_cvt_pk_f32_fp8_e32 v[120:121], v54
	v_cvt_pk_f32_fp8_sdwa v[122:123], v54 src0_sel:WORD_1
	v_cvt_pk_f32_fp8_e32 v[124:125], v55
	v_cvt_pk_f32_fp8_sdwa v[126:127], v55 src0_sel:WORD_1
	v_pk_fma_f32 v[166:167], v[120:121], v[150:151], v[166:167] op_sel:[0,1,0] op_sel_hi:[1,1,1]
	v_pk_fma_f32 v[168:169], v[122:123], v[150:151], v[168:169] op_sel:[0,1,0] op_sel_hi:[1,1,1]
	v_pk_fma_f32 v[170:171], v[124:125], v[150:151], v[170:171] op_sel:[0,1,0] op_sel_hi:[1,1,1]
	v_pk_fma_f32 v[172:173], v[126:127], v[150:151], v[172:173] op_sel:[0,1,0] op_sel_hi:[1,1,1]
	v_lshl_add_u32 v4, v83, 7, v0
	global_load_dwordx4 v[52:55], v4, s[40:41]
	s_waitcnt vmcnt(15)
	v_cvt_pk_f32_fp8_e32 v[120:121], v56
	v_cvt_pk_f32_fp8_sdwa v[122:123], v56 src0_sel:WORD_1
	v_cvt_pk_f32_fp8_e32 v[124:125], v57
	v_cvt_pk_f32_fp8_sdwa v[126:127], v57 src0_sel:WORD_1
	v_pk_fma_f32 v[156:157], v[120:121], v[152:153], v[156:157] op_sel_hi:[1,0,1]
	v_pk_fma_f32 v[158:159], v[122:123], v[152:153], v[158:159] op_sel_hi:[1,0,1]
	v_pk_fma_f32 v[160:161], v[124:125], v[152:153], v[160:161] op_sel_hi:[1,0,1]
	v_pk_fma_f32 v[162:163], v[126:127], v[152:153], v[162:163] op_sel_hi:[1,0,1]
	v_cvt_pk_f32_fp8_e32 v[120:121], v58
	v_cvt_pk_f32_fp8_sdwa v[122:123], v58 src0_sel:WORD_1
	v_cvt_pk_f32_fp8_e32 v[124:125], v59
	v_cvt_pk_f32_fp8_sdwa v[126:127], v59 src0_sel:WORD_1
	v_pk_fma_f32 v[166:167], v[120:121], v[152:153], v[166:167] op_sel_hi:[1,0,1]
	v_pk_fma_f32 v[168:169], v[122:123], v[152:153], v[168:169] op_sel_hi:[1,0,1]
	v_pk_fma_f32 v[170:171], v[124:125], v[152:153], v[170:171] op_sel_hi:[1,0,1]
	v_pk_fma_f32 v[172:173], v[126:127], v[152:153], v[172:173] op_sel_hi:[1,0,1]
	v_lshl_add_u32 v3, v84, 7, v0
	global_load_dwordx4 v[56:59], v3, s[40:41]
	s_waitcnt vmcnt(15)
; DI void phase_peer_v(const Args& a, int layer, int ci) {
;     ...
;             for (int g8 = 0; g8 < 16; ++g8) {
;                 u32x4 nxt[8];
;                 if (g8 < 15) gat_loadh(V, idA, idB, g8 + 1, lo16, nxt); else gat_loadh(V, idAn, idBn, 0, lo16, nxt);
;                 const float ghs = g8 < 8 ? ghA : ghB;
; #pragma unroll
;                 for (int j = 0; j < 8; ++j) { const float gv = __shfl(ghs, (g8 & 7) * 8 + j); axpy16h(acc, gv, cur[j]); if (j & 1) __builtin_amdgcn_sched_barrier(0); }
; #pragma unroll
;                 for (int j = 0; j < 8; ++j) cur[j] = nxt[j];
;             }
;             idA = idAn; idB = idBn;
;             float* hrow = a.out + (size_t)m * D;
;             const int col = ci * 1024 + lane * 16;
;             float ss = 0.f;
; #pragma unroll
;             for (int q = 0; q < 4; ++q) { const f32x4 h = *(const f32x4*)(hrow + col + 4 * q);
;                 acc[4 * q] += h.x; acc[4 * q + 1] += h.y; acc[4 * q + 2] += h.z; acc[4 * q + 3] += h.w; }
;             if (ci == 0) {
; #pragma unroll
;                 for (int q = 0; q < 4; ++q) { f32x4 h; h.x = acc[4 * q]; h.y = acc[4 * q + 1]; h.z = acc[4 * q + 2]; h.w = acc[4 * q + 3]; *(f32x4*)(hrow + col + 4 * q) = h; }
	v_cvt_pk_f32_fp8_e32 v[120:121], v60
	v_cvt_pk_f32_fp8_sdwa v[122:123], v60 src0_sel:WORD_1
	v_cvt_pk_f32_fp8_e32 v[124:125], v61
	v_cvt_pk_f32_fp8_sdwa v[126:127], v61 src0_sel:WORD_1
	v_pk_fma_f32 v[156:157], v[120:121], v[152:153], v[156:157] op_sel:[0,1,0] op_sel_hi:[1,1,1]
	v_pk_fma_f32 v[158:159], v[122:123], v[152:153], v[158:159] op_sel:[0,1,0] op_sel_hi:[1,1,1]
	v_pk_fma_f32 v[160:161], v[124:125], v[152:153], v[160:161] op_sel:[0,1,0] op_sel_hi:[1,1,1]
	v_pk_fma_f32 v[162:163], v[126:127], v[152:153], v[162:163] op_sel:[0,1,0] op_sel_hi:[1,1,1]
	v_cvt_pk_f32_fp8_e32 v[120:121], v62
	v_cvt_pk_f32_fp8_sdwa v[122:123], v62 src0_sel:WORD_1
	v_cvt_pk_f32_fp8_e32 v[124:125], v63
	v_cvt_pk_f32_fp8_sdwa v[126:127], v63 src0_sel:WORD_1
	v_pk_fma_f32 v[166:167], v[120:121], v[152:153], v[166:167] op_sel:[0,1,0] op_sel_hi:[1,1,1]
	v_pk_fma_f32 v[168:169], v[122:123], v[152:153], v[168:169] op_sel:[0,1,0] op_sel_hi:[1,1,1]
	v_pk_fma_f32 v[170:171], v[124:125], v[152:153], v[170:171] op_sel:[0,1,0] op_sel_hi:[1,1,1]
	v_pk_fma_f32 v[172:173], v[126:127], v[152:153], v[172:173] op_sel:[0,1,0] op_sel_hi:[1,1,1]
	v_lshl_add_u32 v4, v85, 7, v0
	global_load_dwordx4 v[60:63], v4, s[40:41]
	s_waitcnt vmcnt(15)
	v_cvt_pk_f32_fp8_e32 v[120:121], v64
	v_cvt_pk_f32_fp8_sdwa v[122:123], v64 src0_sel:WORD_1
	v_cvt_pk_f32_fp8_e32 v[124:125], v65
	v_cvt_pk_f32_fp8_sdwa v[126:127], v65 src0_sel:WORD_1
	v_pk_fma_f32 v[156:157], v[120:121], v[154:155], v[156:157] op_sel_hi:[1,0,1]
	v_pk_fma_f32 v[158:159], v[122:123], v[154:155], v[158:159] op_sel_hi:[1,0,1]
	v_pk_fma_f32 v[160:161], v[124:125], v[154:155], v[160:161] op_sel_hi:[1,0,1]
	v_pk_fma_f32 v[162:163], v[126:127], v[154:155], v[162:163] op_sel_hi:[1,0,1]
	v_cvt_pk_f32_fp8_e32 v[120:121], v66
	v_cvt_pk_f32_fp8_sdwa v[122:123], v66 src0_sel:WORD_1
	v_cvt_pk_f32_fp8_e32 v[124:125], v67
	v_cvt_pk_f32_fp8_sdwa v[126:127], v67 src0_sel:WORD_1
	v_pk_fma_f32 v[166:167], v[120:121], v[154:155], v[166:167] op_sel_hi:[1,0,1]
	v_pk_fma_f32 v[168:169], v[122:123], v[154:155], v[168:169] op_sel_hi:[1,0,1]
	v_pk_fma_f32 v[170:171], v[124:125], v[154:155], v[170:171] op_sel_hi:[1,0,1]
	v_pk_fma_f32 v[172:173], v[126:127], v[154:155], v[172:173] op_sel_hi:[1,0,1]
	v_lshl_add_u32 v3, v86, 7, v0
	global_load_dwordx4 v[64:67], v3, s[40:41]
	s_waitcnt vmcnt(15)
	v_cvt_pk_f32_fp8_e32 v[120:121], v68
	v_cvt_pk_f32_fp8_sdwa v[122:123], v68 src0_sel:WORD_1
	v_cvt_pk_f32_fp8_e32 v[124:125], v69
	v_cvt_pk_f32_fp8_sdwa v[126:127], v69 src0_sel:WORD_1
	v_pk_fma_f32 v[156:157], v[120:121], v[154:155], v[156:157] op_sel:[0,1,0] op_sel_hi:[1,1,1]
	v_pk_fma_f32 v[158:159], v[122:123], v[154:155], v[158:159] op_sel:[0,1,0] op_sel_hi:[1,1,1]
	v_pk_fma_f32 v[160:161], v[124:125], v[154:155], v[160:161] op_sel:[0,1,0] op_sel_hi:[1,1,1]
	v_pk_fma_f32 v[162:163], v[126:127], v[154:155], v[162:163] op_sel:[0,1,0] op_sel_hi:[1,1,1]
	v_cvt_pk_f32_fp8_e32 v[120:121], v70
	v_cvt_pk_f32_fp8_sdwa v[122:123], v70 src0_sel:WORD_1
	v_cvt_pk_f32_fp8_e32 v[124:125], v71
	v_cvt_pk_f32_fp8_sdwa v[126:127], v71 src0_sel:WORD_1
	v_pk_fma_f32 v[166:167], v[120:121], v[154:155], v[166:167] op_sel:[0,1,0] op_sel_hi:[1,1,1]
	v_pk_fma_f32 v[168:169], v[122:123], v[154:155], v[168:169] op_sel:[0,1,0] op_sel_hi:[1,1,1]
	v_pk_fma_f32 v[170:171], v[124:125], v[154:155], v[170:171] op_sel:[0,1,0] op_sel_hi:[1,1,1]
	v_pk_fma_f32 v[172:173], v[126:127], v[154:155], v[172:173] op_sel:[0,1,0] op_sel_hi:[1,1,1]
	v_lshl_add_u32 v4, v87, 7, v0
	global_load_dwordx4 v[68:71], v4, s[40:41]
	s_cmp_eq_u32 s47, 7
	s_cbranch_scc0 .Lpv_b1_nost
	v_pk_add_f32 v[216:217], v[216:217], v[156:157]
	v_pk_add_f32 v[218:219], v[218:219], v[158:159]
	v_pk_add_f32 v[220:221], v[220:221], v[160:161]
	v_pk_add_f32 v[222:223], v[222:223], v[162:163]
	v_pk_add_f32 v[224:225], v[224:225], v[166:167]
	v_pk_add_f32 v[226:227], v[226:227], v[168:169]
	v_pk_add_f32 v[174:175], v[174:175], v[170:171]
	v_pk_add_f32 v[176:177], v[176:177], v[172:173]
	v_mov_b64_e32 v[156:157], 0
	v_mov_b64_e32 v[158:159], 0
	v_mov_b64_e32 v[160:161], 0
	v_mov_b64_e32 v[162:163], 0
	v_mov_b64_e32 v[166:167], 0
	v_mov_b64_e32 v[168:169], 0
	v_mov_b64_e32 v[170:171], 0
	v_mov_b64_e32 v[172:173], 0
	global_store_dwordx4 v2, v[216:219], s[42:43]
	global_store_dwordx4 v2, v[220:223], s[42:43] offset:16
	global_store_dwordx4 v2, v[224:227], s[42:43] offset:32
	global_store_dwordx4 v2, v[174:177], s[42:43] offset:48

; DI void gat_loadhu(const unsigned char* base, int idlo, int idhi, int g8, unsigned lo16, u32x4 (&buf)[8]) {
;     const int ids = g8 < 8 ? idlo : idhi, e0 = (g8 & 7) * 8;
; #pragma unroll
;     for (int j = 0; j < 8; ++j) buf[j] = *(const u32x4*)(base + ((unsigned)__shfl(ids, e0 + j) * (unsigned)D + lo16));
; }
; DI void phase_peer_u(const Args& a, int layer, int ci) {
;     ...
;     int m = gw;
;     if (m < M) {
;         int idA = IDX[(size_t)m * 128 + lane], idB = IDX[(size_t)m * 128 + 64 + lane];
;         u32x4 xa = *(const u32x4*)(XN + (size_t)m * D), xb = *(const u32x4*)(XN + (size_t)m * D + 8);
;         u32x4 cur[8];
;         gat_loadhu(U, idA, idB, 0, lo16, cur);
; #pragma unroll 1
;         for (; m < M; m += NGW) {
;             const int mn = m + NGW < M ? m + NGW : m;
;             const int idAn = IDX[(size_t)mn * 128 + lane], idBn = IDX[(size_t)mn * 128 + 64 + lane];
;             const u32x4 xan = *(const u32x4*)(XN + (size_t)mn * D), xbn = *(const u32x4*)(XN + (size_t)mn * D + 8);
;             float glA = 0.f, glB = 0.f, pdA = 0.f, pdB = 0.f, rstdu = 0.f;
;             if (ci == 1) {
;                 glA = GATE[(size_t)m * 128 + lane] * GSUM[(size_t)m * 8 + (lane >> 4)] * (1.f / V_SCALE);
;                 glB = GATE[(size_t)m * 128 + 64 + lane] * GSUM[(size_t)m * 8 + 4 + (lane >> 4)] * (1.f / V_SCALE);
;                 pdA = PD[(size_t)m * 128 + lane]; pdB = PD[(size_t)m * 128 + 64 + lane];
;                 rstdu = __builtin_bit_cast(float, __builtin_amdgcn_readfirstlane(__builtin_bit_cast(int, rsqrtf(wave_sum(lane < 32 ? ((const float*)(ws + WS_RSS))[((size_t)layer * M + m) * 32 + lane] : 0.f) * (1.f / D) + 1e-6f) * (1.f / U_SCALE))));
;             }
;             float rA = 0.f, rB = 0.f;
; #pragma unroll 1
;             for (int g8 = 0; g8 < 16; ++g8) {
;                 u32x4 nxt[8];
;                 if (g8 < 15) gat_loadhu(U, idA, idB, g8 + 1, lo16, nxt); else gat_loadhu(U, idAn, idBn, 0, lo16, nxt);
.Lpu_entry:
	v_readlane_b32 s1, v252, 0
	v_readlane_b32 s19, v255, 12
	v_lshrrev_b32_e32 v5, 6, v185
	v_and_b32_e32 v6, 63, v185
	v_and_b32_e32 v7, 7, v6
	v_lshrrev_b32_e32 v6, 3, v6
	v_readfirstlane_b32 s44, v5
	v_lshlrev_b32_e32 v0, 4, v7
	v_lshlrev_b32_e32 v1, 9, v6
	v_lshl_or_b32 v2, v7, 4, v1
	v_lshlrev_b32_e32 v236, 12, v6
	v_lshl_or_b32 v236, v7, 5, v236
	v_and_b32_e32 v5, 1, v7
	v_cmp_ne_u32_e64 s[34:35], 0, v5
	v_and_b32_e32 v5, 2, v7
	v_cmp_ne_u32_e64 s[48:49], 0, v5
	v_and_b32_e32 v5, 4, v7
	v_cmp_ne_u32_e64 s[50:51], 0, v5
	s_lshr_b32 s45, s1, 3
	s_lshl_b32 s45, s45, 3
	s_add_u32 s45, s45, s44
	s_lshl_b32 s8, s45, 12
	s_and_b32 s9, s1, 7
	s_lshl_b32 s9, s9, 1
	s_lshl_b32 s46, s19, 25
	s_add_u32 s16, s98, 0x8000000
	s_addc_u32 s17, s99, 0
	s_add_u32 s16, s16, s46
	s_addc_u32 s17, s17, 0
	s_mov_b32 s0, 0
	s_lshl_b32 s1, s44, 14
	v_and_b32_e32 v5, 63, v185
	v_lshlrev_b32_e32 v238, 4, v5
	v_mov_b32_e32 v239, 0
	v_add_u32_e32 v240, s1, v1
	s_mov_b32 s19, 0
	s_and_b32 s45, s19, 15
	s_lshl_b32 s45, s45, 20
	s_add_u32 s45, s45, s8
	s_and_b32 s46, s19, 1
	s_lshl_b32 s46, s46, 12
	s_add_u32 s46, s46, s1
	s_add_u32 s100, s45, 0x6000000
	s_add_u32 s22, s98, s100
	s_addc_u32 s23, s99, 0
	v_lshl_add_u64 v[6:7], s[22:23], 0, v[238:239]
	s_mov_b32 m0, s46
	s_nop 0
	global_load_lds_dwordx4 v[6:7], off
	global_load_lds_dwordx4 v[6:7], off offset:1024
	global_load_lds_dwordx4 v[6:7], off offset:2048
	global_load_lds_dwordx4 v[6:7], off offset:3072
	s_and_b32 s45, s19, 15
	s_lshl_b32 s45, s45, 23
	s_lshl_b32 s46, s8, 3
	s_add_u32 s45, s45, s46
	s_lshr_b32 s46, s19, 4
	s_add_u32 s46, s46, s9
	s_lshl_b32 s46, s46, 8
	s_add_u32 s45, s45, s46
	s_add_u32 s24, s20, s45
	s_addc_u32 s25, s21, 0
	global_load_dwordx4 v[120:123], v236, s[24:25]
	global_load_dwordx4 v[124:127], v236, s[24:25] offset:16
	s_lshr_b32 s46, s0, 7
	s_add_u32 s46, s46, s9
	s_lshl_b32 s46, s46, 21
	s_add_u32 s40, s16, s46
	s_addc_u32 s41, s17, 0
	s_waitcnt vmcnt(0)
	v_lshlrev_b32_e32 v104, 16, v120
	v_and_b32_e32 v105, 0xffff0000, v120
	v_lshlrev_b32_e32 v106, 16, v121
	v_and_b32_e32 v107, 0xffff0000, v121
	v_lshlrev_b32_e32 v108, 16, v122
	v_and_b32_e32 v109, 0xffff0000, v122
	v_lshlrev_b32_e32 v110, 16, v123
	v_and_b32_e32 v111, 0xffff0000, v123
	v_lshlrev_b32_e32 v112, 16, v124
	v_and_b32_e32 v113, 0xffff0000, v124
	v_lshlrev_b32_e32 v114, 16, v125
	v_and_b32_e32 v115, 0xffff0000, v125
	v_lshlrev_b32_e32 v116, 16, v126
	v_and_b32_e32 v117, 0xffff0000, v126
	v_lshlrev_b32_e32 v118, 16, v127
	v_and_b32_e32 v119, 0xffff0000, v127
	s_mov_b32 s44, 0
	s_bfe_u32 s45, s44, 0x10003
	s_lshl_b32 s45, s45, 12
	s_and_b32 s46, s44, 7
	s_lshl_b32 s46, s46, 6
	s_add_u32 s45, s45, s46
	v_add_u32_e32 v5, s45, v240
	ds_read_b128 v[72:75], v5
	ds_read_b128 v[76:79], v5 offset:16
	ds_read_b128 v[80:83], v5 offset:32
	ds_read_b128 v[84:87], v5 offset:48
	s_mov_b32 s44, 1
	s_bfe_u32 s45, s44, 0x10003
	s_lshl_b32 s45, s45, 12
	s_and_b32 s46, s44, 7
	s_lshl_b32 s46, s46, 6
	s_add_u32 s45, s45, s46
	v_add_u32_e32 v5, s45, v240
	ds_read_b128 v[88:91], v5
	ds_read_b128 v[92:95], v5 offset:16
	ds_read_b128 v[96:99], v5 offset:32
	ds_read_b128 v[100:103], v5 offset:48
	s_waitcnt lgkmcnt(0)
	v_lshl_add_u32 v3, v72, 7, v0
	global_load_dwordx4 v[8:11], v3, s[40:41]
	v_lshl_add_u32 v4, v73, 7, v0
	global_load_dwordx4 v[12:15], v4, s[40:41]
	v_lshl_add_u32 v3, v74, 7, v0
	global_load_dwordx4 v[16:19], v3, s[40:41]
	v_lshl_add_u32 v4, v75, 7, v0
	global_load_dwordx4 v[20:23], v4, s[40:41]
	v_lshl_add_u32 v3, v76, 7, v0
	global_load_dwordx4 v[24:27], v3, s[40:41]
	v_lshl_add_u32 v4, v77, 7, v0
	global_load_dwordx4 v[28:31], v4, s[40:41]
	v_lshl_add_u32 v3, v78, 7, v0
	global_load_dwordx4 v[32:35], v3, s[40:41]
	v_lshl_add_u32 v4, v79, 7, v0
	global_load_dwordx4 v[36:39], v4, s[40:41]
	v_lshl_add_u32 v3, v80, 7, v0
	global_load_dwordx4 v[40:43], v3, s[40:41]
	v_lshl_add_u32 v4, v81, 7, v0
	global_load_dwordx4 v[44:47], v4, s[40:41]
	v_lshl_add_u32 v3, v82, 7, v0
	global_load_dwordx4 v[48:51], v3, s[40:41]
	v_lshl_add_u32 v4, v83, 7, v0
	global_load_dwordx4 v[52:55], v4, s[40:41]
	v_lshl_add_u32 v3, v84, 7, v0
	global_load_dwordx4 v[56:59], v3, s[40:41]
	v_lshl_add_u32 v4, v85, 7, v0
	global_load_dwordx4 v[60:63], v4, s[40:41]
	v_lshl_add_u32 v3, v86, 7, v0
	global_load_dwordx4 v[64:67], v3, s[40:41]
	v_lshl_add_u32 v4, v87, 7, v0
	global_load_dwordx4 v[68:71], v4, s[40:41]
.Lpu_loop:
	s_add_u32 s44, s0, 1
	s_min_u32 s44, s44, 0xff
	s_lshr_b32 s46, s44, 7
	s_add_u32 s46, s46, s9
	s_lshl_b32 s46, s46, 21
	s_add_u32 s40, s16, s46
	s_addc_u32 s41, s17, 0
	s_and_b32 s47, s0, 7
	s_cmp_eq_u32 s47, 0
	s_cbranch_scc0 .Lpu_b0_nox
	s_lshr_b32 s19, s0, 3
	s_add_u32 s19, s19, 1
	s_min_u32 s19, s19, 31
	s_and_b32 s45, s19, 15
	s_lshl_b32 s45, s45, 20
	s_add_u32 s45, s45, s8
	s_and_b32 s46, s19, 1
	s_lshl_b32 s46, s46, 12
	s_add_u32 s46, s46, s1
	s_add_u32 s100, s45, 0x6000000
	s_add_u32 s22, s98, s100
	s_addc_u32 s23, s99, 0
	v_lshl_add_u64 v[6:7], s[22:23], 0, v[238:239]
	s_mov_b32 m0, s46
	s_nop 0
	global_load_lds_dwordx4 v[6:7], off
	global_load_lds_dwordx4 v[6:7], off offset:1024
	global_load_lds_dwordx4 v[6:7], off offset:2048
	global_load_lds_dwordx4 v[6:7], off offset:3072
	s_and_b32 s45, s19, 15
	s_lshl_b32 s45, s45, 23
	s_lshl_b32 s46, s8, 3
	s_add_u32 s45, s45, s46
	s_lshr_b32 s46, s19, 4
	s_add_u32 s46, s46, s9
	s_lshl_b32 s46, s46, 8
	s_add_u32 s45, s45, s46
	s_add_u32 s24, s20, s45
	s_addc_u32 s25, s21, 0
	global_load_dwordx4 v[120:123], v236, s[24:25]
	global_load_dwordx4 v[124:127], v236, s[24:25] offset:16
; #define FP8_LO(w) __builtin_amdgcn_cvt_pk_f32_fp8((int)(w), false)
; #define FP8_HI(w) __builtin_amdgcn_cvt_pk_f32_fp8((int)(w), true)
; DI float dot16p(const u32x4 xa, const u32x4 xb, const u32x4 w) {
;     const f32x2 a0 = FP8_LO(w.x), a1 = FP8_HI(w.x), a2 = FP8_LO(w.y), a3 = FP8_HI(w.y), a4 = FP8_LO(w.z), a5 = FP8_HI(w.z), a6 = FP8_LO(w.w), a7 = FP8_HI(w.w);
;     return (bflo(xa.x) * a0.x + bfhi(xa.x) * a0.y + bflo(xa.y) * a1.x + bfhi(xa.y) * a1.y) + (bflo(xa.z) * a2.x + bfhi(xa.z) * a2.y + bflo(xa.w) * a3.x + bfhi(xa.w) * a3.y)
;          + (bflo(xb.x) * a4.x + bfhi(xb.x) * a4.y + bflo(xb.y) * a5.x + bfhi(xb.y) * a5.y) + (bflo(xb.z) * a6.x + bfhi(xb.z) * a6.y + bflo(xb.w) * a7.x + bfhi(xb.w) * a7.y);
; }
; DI void phase_peer_u(const Args& a, int layer, int ci) {
;     ...
;             for (int g8 = 0; g8 < 16; ++g8) {
;                 u32x4 nxt[8];
;                 if (g8 < 15) gat_loadhu(U, idA, idB, g8 + 1, lo16, nxt); else gat_loadhu(U, idAn, idBn, 0, lo16, nxt);
;                 const float c0 = dots4h(xa, xb, cur[0], cur[1], cur[2], cur[3], lane);
;                 const float c1 = dots4h(xa, xb, cur[4], cur[5], cur[6], cur[7], lane);
.Lpu_b0_nox:
	s_waitcnt lgkmcnt(0)
	s_add_u32 s44, s0, 2
	s_min_u32 s44, s44, 0xff
	s_bfe_u32 s45, s44, 0x10003
	s_lshl_b32 s45, s45, 12
	s_and_b32 s46, s44, 7
	s_lshl_b32 s46, s46, 6
	s_add_u32 s45, s45, s46
	v_add_u32_e32 v5, s45, v240
	ds_read_b128 v[72:75], v5
	ds_read_b128 v[76:79], v5 offset:16
	ds_read_b128 v[80:83], v5 offset:32
	ds_read_b128 v[84:87], v5 offset:48
	s_waitcnt vmcnt(15)
	v_cvt_pk_f32_fp8_e32 v[140:141], v8
	v_cvt_pk_f32_fp8_sdwa v[142:143], v8 src0_sel:WORD_1
	v_cvt_pk_f32_fp8_e32 v[144:145], v9
	v_cvt_pk_f32_fp8_sdwa v[146:147], v9 src0_sel:WORD_1
	v_pk_mul_f32 v[148:149], v[140:141], v[104:105]
	v_pk_mul_f32 v[150:151], v[142:143], v[106:107]
	v_pk_fma_f32 v[148:149], v[144:145], v[108:109], v[148:149]
	v_pk_fma_f32 v[150:151], v[146:147], v[110:111], v[150:151]
	v_cvt_pk_f32_fp8_e32 v[140:141], v10
	v_cvt_pk_f32_fp8_sdwa v[142:143], v10 src0_sel:WORD_1
	v_cvt_pk_f32_fp8_e32 v[144:145], v11
	v_cvt_pk_f32_fp8_sdwa v[146:147], v11 src0_sel:WORD_1
	v_pk_fma_f32 v[148:149], v[140:141], v[112:113], v[148:149]
	v_pk_fma_f32 v[150:151], v[142:143], v[114:115], v[150:151]
	v_pk_fma_f32 v[148:149], v[144:145], v[116:117], v[148:149]
	v_pk_fma_f32 v[150:151], v[146:147], v[118:119], v[150:151]
	v_pk_add_f32 v[148:149], v[148:149], v[150:151]
	s_nop 0
	v_add_f32_e32 v156, v148, v149
	v_lshl_add_u32 v3, v88, 7, v0
	global_load_dwordx4 v[8:11], v3, s[40:41]
	s_waitcnt vmcnt(15)
	v_cvt_pk_f32_fp8_e32 v[140:141], v12
	v_cvt_pk_f32_fp8_sdwa v[142:143], v12 src0_sel:WORD_1
	v_cvt_pk_f32_fp8_e32 v[144:145], v13
	v_cvt_pk_f32_fp8_sdwa v[146:147], v13 src0_sel:WORD_1
	v_pk_mul_f32 v[148:149], v[140:141], v[104:105]
	v_pk_mul_f32 v[150:151], v[142:143], v[106:107]
	v_pk_fma_f32 v[148:149], v[144:145], v[108:109], v[148:149]
	v_pk_fma_f32 v[150:151], v[146:147], v[110:111], v[150:151]
	v_cvt_pk_f32_fp8_e32 v[140:141], v14
	v_cvt_pk_f32_fp8_sdwa v[142:143], v14 src0_sel:WORD_1
	v_cvt_pk_f32_fp8_e32 v[144:145], v15
	v_cvt_pk_f32_fp8_sdwa v[146:147], v15 src0_sel:WORD_1
	v_pk_fma_f32 v[148:149], v[140:141], v[112:113], v[148:149]
	v_pk_fma_f32 v[150:151], v[142:143], v[114:115], v[150:151]
	v_pk_fma_f32 v[148:149], v[144:145], v[116:117], v[148:149]
	v_pk_fma_f32 v[150:151], v[146:147], v[118:119], v[150:151]
	v_pk_add_f32 v[148:149], v[148:149], v[150:151]
	s_nop 0
	v_add_f32_e32 v157, v148, v149
	v_lshl_add_u32 v4, v89, 7, v0
	global_load_dwordx4 v[12:15], v4, s[40:41]
	s_waitcnt vmcnt(15)
	v_cvt_pk_f32_fp8_e32 v[140:141], v16
	v_cvt_pk_f32_fp8_sdwa v[142:143], v16 src0_sel:WORD_1
	v_cvt_pk_f32_fp8_e32 v[144:145], v17
	v_cvt_pk_f32_fp8_sdwa v[146:147], v17 src0_sel:WORD_1
	v_pk_mul_f32 v[148:149], v[140:141], v[104:105]
	v_pk_mul_f32 v[150:151], v[142:143], v[106:107]
	v_pk_fma_f32 v[148:149], v[144:145], v[108:109], v[148:149]
	v_pk_fma_f32 v[150:151], v[146:147], v[110:111], v[150:151]
	v_cvt_pk_f32_fp8_e32 v[140:141], v18
	v_cvt_pk_f32_fp8_sdwa v[142:143], v18 src0_sel:WORD_1
	v_cvt_pk_f32_fp8_e32 v[144:145], v19
	v_cvt_pk_f32_fp8_sdwa v[146:147], v19 src0_sel:WORD_1
	v_pk_fma_f32 v[148:149], v[140:141], v[112:113], v[148:149]
	v_pk_fma_f32 v[150:151], v[142:143], v[114:115], v[150:151]
	v_pk_fma_f32 v[148:149], v[144:145], v[116:117], v[148:149]
	v_pk_fma_f32 v[150:151], v[146:147], v[118:119], v[150:151]
	v_pk_add_f32 v[148:149], v[148:149], v[150:151]
	s_nop 0
	v_add_f32_e32 v158, v148, v149
	v_lshl_add_u32 v3, v90, 7, v0
	global_load_dwordx4 v[16:19], v3, s[40:41]
	s_waitcnt vmcnt(15)
	v_cvt_pk_f32_fp8_e32 v[140:141], v20
	v_cvt_pk_f32_fp8_sdwa v[142:143], v20 src0_sel:WORD_1
	v_cvt_pk_f32_fp8_e32 v[144:145], v21
	v_cvt_pk_f32_fp8_sdwa v[146:147], v21 src0_sel:WORD_1
	v_pk_mul_f32 v[148:149], v[140:141], v[104:105]
	v_pk_mul_f32 v[150:151], v[142:143], v[106:107]
	v_pk_fma_f32 v[148:149], v[144:145], v[108:109], v[148:149]
	v_pk_fma_f32 v[150:151], v[146:147], v[110:111], v[150:151]
	v_cvt_pk_f32_fp8_e32 v[140:141], v22
	v_cvt_pk_f32_fp8_sdwa v[142:143], v22 src0_sel:WORD_1
	v_cvt_pk_f32_fp8_e32 v[144:145], v23
	v_cvt_pk_f32_fp8_sdwa v[146:147], v23 src0_sel:WORD_1
	v_pk_fma_f32 v[148:149], v[140:141], v[112:113], v[148:149]
	v_pk_fma_f32 v[150:151], v[142:143], v[114:115], v[150:151]
	v_pk_fma_f32 v[148:149], v[144:145], v[116:117], v[148:149]
	v_pk_fma_f32 v[150:151], v[146:147], v[118:119], v[150:151]
	v_pk_add_f32 v[148:149], v[148:149], v[150:151]
	s_nop 0
	v_add_f32_e32 v159, v148, v149
	v_lshl_add_u32 v4, v91, 7, v0
	global_load_dwordx4 v[20:23], v4, s[40:41]
	s_waitcnt vmcnt(15)
	v_cvt_pk_f32_fp8_e32 v[140:141], v24
	v_cvt_pk_f32_fp8_sdwa v[142:143], v24 src0_sel:WORD_1
	v_cvt_pk_f32_fp8_e32 v[144:145], v25
	v_cvt_pk_f32_fp8_sdwa v[146:147], v25 src0_sel:WORD_1
	v_pk_mul_f32 v[148:149], v[140:141], v[104:105]
	v_pk_mul_f32 v[150:151], v[142:143], v[106:107]
	v_pk_fma_f32 v[148:149], v[144:145], v[108:109], v[148:149]
	v_pk_fma_f32 v[150:151], v[146:147], v[110:111], v[150:151]
	v_cvt_pk_f32_fp8_e32 v[140:141], v26
	v_cvt_pk_f32_fp8_sdwa v[142:143], v26 src0_sel:WORD_1
	v_cvt_pk_f32_fp8_e32 v[144:145], v27
	v_cvt_pk_f32_fp8_sdwa v[146:147], v27 src0_sel:WORD_1
	v_pk_fma_f32 v[148:149], v[140:141], v[112:113], v[148:149]
	v_pk_fma_f32 v[150:151], v[142:143], v[114:115], v[150:151]
	v_pk_fma_f32 v[148:149], v[144:145], v[116:117], v[148:149]
	v_pk_fma_f32 v[150:151], v[146:147], v[118:119], v[150:151]
	v_pk_add_f32 v[148:149], v[148:149], v[150:151]
	s_nop 0
	v_add_f32_e32 v160, v148, v149
	v_lshl_add_u32 v3, v92, 7, v0
	global_load_dwordx4 v[24:27], v3, s[40:41]
	s_waitcnt vmcnt(15)
; #define FP8_LO(w) __builtin_amdgcn_cvt_pk_f32_fp8((int)(w), false)
; #define FP8_HI(w) __builtin_amdgcn_cvt_pk_f32_fp8((int)(w), true)
; DI float dot16p(const u32x4 xa, const u32x4 xb, const u32x4 w) {
;     const f32x2 a0 = FP8_LO(w.x), a1 = FP8_HI(w.x), a2 = FP8_LO(w.y), a3 = FP8_HI(w.y), a4 = FP8_LO(w.z), a5 = FP8_HI(w.z), a6 = FP8_LO(w.w), a7 = FP8_HI(w.w);
;     return (bflo(xa.x) * a0.x + bfhi(xa.x) * a0.y + bflo(xa.y) * a1.x + bfhi(xa.y) * a1.y) + (bflo(xa.z) * a2.x + bfhi(xa.z) * a2.y + bflo(xa.w) * a3.x + bfhi(xa.w) * a3.y)
;          + (bflo(xb.x) * a4.x + bfhi(xb.x) * a4.y + bflo(xb.y) * a5.x + bfhi(xb.y) * a5.y) + (bflo(xb.z) * a6.x + bfhi(xb.z) * a6.y + bflo(xb.w) * a7.x + bfhi(xb.w) * a7.y);
; }
; DI void phase_peer_u(const Args& a, int layer, int ci) {
;     ...
;                 const float c0 = dots4h(xa, xb, cur[0], cur[1], cur[2], cur[3], lane);
;                 const float c1 = dots4h(xa, xb, cur[4], cur[5], cur[6], cur[7], lane);
	v_cvt_pk_f32_fp8_e32 v[140:141], v28
	v_cvt_pk_f32_fp8_sdwa v[142:143], v28 src0_sel:WORD_1
	v_cvt_pk_f32_fp8_e32 v[144:145], v29
	v_cvt_pk_f32_fp8_sdwa v[146:147], v29 src0_sel:WORD_1
	v_pk_mul_f32 v[148:149], v[140:141], v[104:105]
	v_pk_mul_f32 v[150:151], v[142:143], v[106:107]
	v_pk_fma_f32 v[148:149], v[144:145], v[108:109], v[148:149]
	v_pk_fma_f32 v[150:151], v[146:147], v[110:111], v[150:151]
	v_cvt_pk_f32_fp8_e32 v[140:141], v30
	v_cvt_pk_f32_fp8_sdwa v[142:143], v30 src0_sel:WORD_1
	v_cvt_pk_f32_fp8_e32 v[144:145], v31
	v_cvt_pk_f32_fp8_sdwa v[146:147], v31 src0_sel:WORD_1
	v_pk_fma_f32 v[148:149], v[140:141], v[112:113], v[148:149]
	v_pk_fma_f32 v[150:151], v[142:143], v[114:115], v[150:151]
	v_pk_fma_f32 v[148:149], v[144:145], v[116:117], v[148:149]
	v_pk_fma_f32 v[150:151], v[146:147], v[118:119], v[150:151]
	v_pk_add_f32 v[148:149], v[148:149], v[150:151]
	s_nop 0
	v_add_f32_e32 v161, v148, v149
	v_lshl_add_u32 v4, v93, 7, v0
	global_load_dwordx4 v[28:31], v4, s[40:41]
	s_waitcnt vmcnt(15)
	v_cvt_pk_f32_fp8_e32 v[140:141], v32
	v_cvt_pk_f32_fp8_sdwa v[142:143], v32 src0_sel:WORD_1
	v_cvt_pk_f32_fp8_e32 v[144:145], v33
	v_cvt_pk_f32_fp8_sdwa v[146:147], v33 src0_sel:WORD_1
	v_pk_mul_f32 v[148:149], v[140:141], v[104:105]
	v_pk_mul_f32 v[150:151], v[142:143], v[106:107]
	v_pk_fma_f32 v[148:149], v[144:145], v[108:109], v[148:149]
	v_pk_fma_f32 v[150:151], v[146:147], v[110:111], v[150:151]
	v_cvt_pk_f32_fp8_e32 v[140:141], v34
	v_cvt_pk_f32_fp8_sdwa v[142:143], v34 src0_sel:WORD_1
	v_cvt_pk_f32_fp8_e32 v[144:145], v35
	v_cvt_pk_f32_fp8_sdwa v[146:147], v35 src0_sel:WORD_1
	v_pk_fma_f32 v[148:149], v[140:141], v[112:113], v[148:149]
	v_pk_fma_f32 v[150:151], v[142:143], v[114:115], v[150:151]
	v_pk_fma_f32 v[148:149], v[144:145], v[116:117], v[148:149]
	v_pk_fma_f32 v[150:151], v[146:147], v[118:119], v[150:151]
	v_pk_add_f32 v[148:149], v[148:149], v[150:151]
	s_nop 0
	v_add_f32_e32 v162, v148, v149
	v_lshl_add_u32 v3, v94, 7, v0
	global_load_dwordx4 v[32:35], v3, s[40:41]
	s_waitcnt vmcnt(15)
	v_cvt_pk_f32_fp8_e32 v[140:141], v36
	v_cvt_pk_f32_fp8_sdwa v[142:143], v36 src0_sel:WORD_1
	v_cvt_pk_f32_fp8_e32 v[144:145], v37
	v_cvt_pk_f32_fp8_sdwa v[146:147], v37 src0_sel:WORD_1
	v_pk_mul_f32 v[148:149], v[140:141], v[104:105]
	v_pk_mul_f32 v[150:151], v[142:143], v[106:107]
	v_pk_fma_f32 v[148:149], v[144:145], v[108:109], v[148:149]
	v_pk_fma_f32 v[150:151], v[146:147], v[110:111], v[150:151]
	v_cvt_pk_f32_fp8_e32 v[140:141], v38
	v_cvt_pk_f32_fp8_sdwa v[142:143], v38 src0_sel:WORD_1
	v_cvt_pk_f32_fp8_e32 v[144:145], v39
	v_cvt_pk_f32_fp8_sdwa v[146:147], v39 src0_sel:WORD_1
	v_pk_fma_f32 v[148:149], v[140:141], v[112:113], v[148:149]
	v_pk_fma_f32 v[150:151], v[142:143], v[114:115], v[150:151]
	v_pk_fma_f32 v[148:149], v[144:145], v[116:117], v[148:149]
	v_pk_fma_f32 v[150:151], v[146:147], v[118:119], v[150:151]
	v_pk_add_f32 v[148:149], v[148:149], v[150:151]
	s_nop 0
	v_add_f32_e32 v163, v148, v149
	v_lshl_add_u32 v4, v95, 7, v0
	global_load_dwordx4 v[36:39], v4, s[40:41]
	s_waitcnt vmcnt(15)
	v_cvt_pk_f32_fp8_e32 v[140:141], v40
	v_cvt_pk_f32_fp8_sdwa v[142:143], v40 src0_sel:WORD_1
	v_cvt_pk_f32_fp8_e32 v[144:145], v41
	v_cvt_pk_f32_fp8_sdwa v[146:147], v41 src0_sel:WORD_1
	v_pk_mul_f32 v[148:149], v[140:141], v[104:105]
	v_pk_mul_f32 v[150:151], v[142:143], v[106:107]
	v_pk_fma_f32 v[148:149], v[144:145], v[108:109], v[148:149]
	v_pk_fma_f32 v[150:151], v[146:147], v[110:111], v[150:151]
	v_cvt_pk_f32_fp8_e32 v[140:141], v42
	v_cvt_pk_f32_fp8_sdwa v[142:143], v42 src0_sel:WORD_1
	v_cvt_pk_f32_fp8_e32 v[144:145], v43
	v_cvt_pk_f32_fp8_sdwa v[146:147], v43 src0_sel:WORD_1
	v_pk_fma_f32 v[148:149], v[140:141], v[112:113], v[148:149]
	v_pk_fma_f32 v[150:151], v[142:143], v[114:115], v[150:151]
	v_pk_fma_f32 v[148:149], v[144:145], v[116:117], v[148:149]
	v_pk_fma_f32 v[150:151], v[146:147], v[118:119], v[150:151]
	v_pk_add_f32 v[148:149], v[148:149], v[150:151]
	s_nop 0
	v_add_f32_e32 v166, v148, v149
	v_lshl_add_u32 v3, v96, 7, v0
	global_load_dwordx4 v[40:43], v3, s[40:41]
	s_waitcnt vmcnt(15)
	v_cvt_pk_f32_fp8_e32 v[140:141], v44
	v_cvt_pk_f32_fp8_sdwa v[142:143], v44 src0_sel:WORD_1
	v_cvt_pk_f32_fp8_e32 v[144:145], v45
	v_cvt_pk_f32_fp8_sdwa v[146:147], v45 src0_sel:WORD_1
	v_pk_mul_f32 v[148:149], v[140:141], v[104:105]
	v_pk_mul_f32 v[150:151], v[142:143], v[106:107]
	v_pk_fma_f32 v[148:149], v[144:145], v[108:109], v[148:149]
	v_pk_fma_f32 v[150:151], v[146:147], v[110:111], v[150:151]
	v_cvt_pk_f32_fp8_e32 v[140:141], v46
	v_cvt_pk_f32_fp8_sdwa v[142:143], v46 src0_sel:WORD_1
	v_cvt_pk_f32_fp8_e32 v[144:145], v47
	v_cvt_pk_f32_fp8_sdwa v[146:147], v47 src0_sel:WORD_1
	v_pk_fma_f32 v[148:149], v[140:141], v[112:113], v[148:149]
	v_pk_fma_f32 v[150:151], v[142:143], v[114:115], v[150:151]
	v_pk_fma_f32 v[148:149], v[144:145], v[116:117], v[148:149]
	v_pk_fma_f32 v[150:151], v[146:147], v[118:119], v[150:151]
	v_pk_add_f32 v[148:149], v[148:149], v[150:151]
	s_nop 0
	v_add_f32_e32 v167, v148, v149
	v_lshl_add_u32 v4, v97, 7, v0
	global_load_dwordx4 v[44:47], v4, s[40:41]
	s_waitcnt vmcnt(15)
	v_cvt_pk_f32_fp8_e32 v[140:141], v48
	v_cvt_pk_f32_fp8_sdwa v[142:143], v48 src0_sel:WORD_1
	v_cvt_pk_f32_fp8_e32 v[144:145], v49
	v_cvt_pk_f32_fp8_sdwa v[146:147], v49 src0_sel:WORD_1
	v_pk_mul_f32 v[148:149], v[140:141], v[104:105]
	v_pk_mul_f32 v[150:151], v[142:143], v[106:107]
	v_pk_fma_f32 v[148:149], v[144:145], v[108:109], v[148:149]
	v_pk_fma_f32 v[150:151], v[146:147], v[110:111], v[150:151]
	v_cvt_pk_f32_fp8_e32 v[140:141], v50
	v_cvt_pk_f32_fp8_sdwa v[142:143], v50 src0_sel:WORD_1
	v_cvt_pk_f32_fp8_e32 v[144:145], v51
	v_cvt_pk_f32_fp8_sdwa v[146:147], v51 src0_sel:WORD_1
	v_pk_fma_f32 v[148:149], v[140:141], v[112:113], v[148:149]
	v_pk_fma_f32 v[150:151], v[142:143], v[114:115], v[150:151]
	v_pk_fma_f32 v[148:149], v[144:145], v[116:117], v[148:149]
	v_pk_fma_f32 v[150:151], v[146:147], v[118:119], v[150:151]
	v_pk_add_f32 v[148:149], v[148:149], v[150:151]
	s_nop 0
	v_add_f32_e32 v168, v148, v149
	v_lshl_add_u32 v3, v98, 7, v0
	global_load_dwordx4 v[48:51], v3, s[40:41]
	s_waitcnt vmcnt(15)
; DI float dots4h(const u32x4 xa, const u32x4 xb, const u32x4 b0, const u32x4 b1, const u32x4 b2, const u32x4 b3, int lane) {
;     const float d0 = dot16p(xa, xb, b0), d1 = dot16p(xa, xb, b1); __builtin_amdgcn_sched_barrier(0);
;     const float d2 = dot16p(xa, xb, b2), d3 = dot16p(xa, xb, b3); __builtin_amdgcn_sched_barrier(0);
;     const bool p1 = lane & 1, p2 = lane & 2;
;     const float b0s = (p1 ? d1 : d0) + __shfl_xor(p1 ? d0 : d1, 1);
;     const float b1s = (p1 ? d3 : d2) + __shfl_xor(p1 ? d2 : d3, 1);
;     float cs = (p2 ? b1s : b0s) + __shfl_xor(p2 ? b0s : b1s, 2);
;     cs += __shfl_xor(cs, 4); cs += __shfl_xor(cs, 8); cs += __shfl_xor(cs, 16); cs += __shfl_xor(cs, 32);
;     return cs;
; DI void phase_peer_u(const Args& a, int layer, int ci) {
;     ...
;                 const float c0 = dots4h(xa, xb, cur[0], cur[1], cur[2], cur[3], lane);
;                 const float c1 = dots4h(xa, xb, cur[4], cur[5], cur[6], cur[7], lane);
;                 const int q4 = (g8 & 7) * 2;
;                 const float cv = (lane >> 2) == q4 ? c0 : c1;
	v_cvt_pk_f32_fp8_e32 v[140:141], v52
	v_cvt_pk_f32_fp8_sdwa v[142:143], v52 src0_sel:WORD_1
	v_cvt_pk_f32_fp8_e32 v[144:145], v53
	v_cvt_pk_f32_fp8_sdwa v[146:147], v53 src0_sel:WORD_1
	v_pk_mul_f32 v[148:149], v[140:141], v[104:105]
	v_pk_mul_f32 v[150:151], v[142:143], v[106:107]
	v_pk_fma_f32 v[148:149], v[144:145], v[108:109], v[148:149]
	v_pk_fma_f32 v[150:151], v[146:147], v[110:111], v[150:151]
	v_cvt_pk_f32_fp8_e32 v[140:141], v54
	v_cvt_pk_f32_fp8_sdwa v[142:143], v54 src0_sel:WORD_1
	v_cvt_pk_f32_fp8_e32 v[144:145], v55
	v_cvt_pk_f32_fp8_sdwa v[146:147], v55 src0_sel:WORD_1
	v_pk_fma_f32 v[148:149], v[140:141], v[112:113], v[148:149]
	v_pk_fma_f32 v[150:151], v[142:143], v[114:115], v[150:151]
	v_pk_fma_f32 v[148:149], v[144:145], v[116:117], v[148:149]
	v_pk_fma_f32 v[150:151], v[146:147], v[118:119], v[150:151]
	v_pk_add_f32 v[148:149], v[148:149], v[150:151]
	s_nop 0
	v_add_f32_e32 v169, v148, v149
	v_lshl_add_u32 v4, v99, 7, v0
	global_load_dwordx4 v[52:55], v4, s[40:41]
	s_waitcnt vmcnt(15)
	v_cvt_pk_f32_fp8_e32 v[140:141], v56
	v_cvt_pk_f32_fp8_sdwa v[142:143], v56 src0_sel:WORD_1
	v_cvt_pk_f32_fp8_e32 v[144:145], v57
	v_cvt_pk_f32_fp8_sdwa v[146:147], v57 src0_sel:WORD_1
	v_pk_mul_f32 v[148:149], v[140:141], v[104:105]
	v_pk_mul_f32 v[150:151], v[142:143], v[106:107]
	v_pk_fma_f32 v[148:149], v[144:145], v[108:109], v[148:149]
	v_pk_fma_f32 v[150:151], v[146:147], v[110:111], v[150:151]
	v_cvt_pk_f32_fp8_e32 v[140:141], v58
	v_cvt_pk_f32_fp8_sdwa v[142:143], v58 src0_sel:WORD_1
	v_cvt_pk_f32_fp8_e32 v[144:145], v59
	v_cvt_pk_f32_fp8_sdwa v[146:147], v59 src0_sel:WORD_1
	v_pk_fma_f32 v[148:149], v[140:141], v[112:113], v[148:149]
	v_pk_fma_f32 v[150:151], v[142:143], v[114:115], v[150:151]
	v_pk_fma_f32 v[148:149], v[144:145], v[116:117], v[148:149]
	v_pk_fma_f32 v[150:151], v[146:147], v[118:119], v[150:151]
	v_pk_add_f32 v[148:149], v[148:149], v[150:151]
	s_nop 0
	v_add_f32_e32 v170, v148, v149
	v_lshl_add_u32 v3, v100, 7, v0
	global_load_dwordx4 v[56:59], v3, s[40:41]
	s_waitcnt vmcnt(15)
	v_cvt_pk_f32_fp8_e32 v[140:141], v60
	v_cvt_pk_f32_fp8_sdwa v[142:143], v60 src0_sel:WORD_1
	v_cvt_pk_f32_fp8_e32 v[144:145], v61
	v_cvt_pk_f32_fp8_sdwa v[146:147], v61 src0_sel:WORD_1
	v_pk_mul_f32 v[148:149], v[140:141], v[104:105]
	v_pk_mul_f32 v[150:151], v[142:143], v[106:107]
	v_pk_fma_f32 v[148:149], v[144:145], v[108:109], v[148:149]
	v_pk_fma_f32 v[150:151], v[146:147], v[110:111], v[150:151]
	v_cvt_pk_f32_fp8_e32 v[140:141], v62
	v_cvt_pk_f32_fp8_sdwa v[142:143], v62 src0_sel:WORD_1
	v_cvt_pk_f32_fp8_e32 v[144:145], v63
	v_cvt_pk_f32_fp8_sdwa v[146:147], v63 src0_sel:WORD_1
	v_pk_fma_f32 v[148:149], v[140:141], v[112:113], v[148:149]
	v_pk_fma_f32 v[150:151], v[142:143], v[114:115], v[150:151]
	v_pk_fma_f32 v[148:149], v[144:145], v[116:117], v[148:149]
	v_pk_fma_f32 v[150:151], v[146:147], v[118:119], v[150:151]
	v_pk_add_f32 v[148:149], v[148:149], v[150:151]
	s_nop 0
	v_add_f32_e32 v171, v148, v149
	v_lshl_add_u32 v4, v101, 7, v0
	global_load_dwordx4 v[60:63], v4, s[40:41]
	s_waitcnt vmcnt(15)
	v_cvt_pk_f32_fp8_e32 v[140:141], v64
	v_cvt_pk_f32_fp8_sdwa v[142:143], v64 src0_sel:WORD_1
	v_cvt_pk_f32_fp8_e32 v[144:145], v65
	v_cvt_pk_f32_fp8_sdwa v[146:147], v65 src0_sel:WORD_1
	v_pk_mul_f32 v[148:149], v[140:141], v[104:105]
	v_pk_mul_f32 v[150:151], v[142:143], v[106:107]
	v_pk_fma_f32 v[148:149], v[144:145], v[108:109], v[148:149]
	v_pk_fma_f32 v[150:151], v[146:147], v[110:111], v[150:151]
	v_cvt_pk_f32_fp8_e32 v[140:141], v66
	v_cvt_pk_f32_fp8_sdwa v[142:143], v66 src0_sel:WORD_1
	v_cvt_pk_f32_fp8_e32 v[144:145], v67
	v_cvt_pk_f32_fp8_sdwa v[146:147], v67 src0_sel:WORD_1
	v_pk_fma_f32 v[148:149], v[140:141], v[112:113], v[148:149]
	v_pk_fma_f32 v[150:151], v[142:143], v[114:115], v[150:151]
	v_pk_fma_f32 v[148:149], v[144:145], v[116:117], v[148:149]
	v_pk_fma_f32 v[150:151], v[146:147], v[118:119], v[150:151]
	v_pk_add_f32 v[148:149], v[148:149], v[150:151]
	s_nop 0
	v_add_f32_e32 v172, v148, v149
	v_lshl_add_u32 v3, v102, 7, v0
	global_load_dwordx4 v[64:67], v3, s[40:41]
	s_waitcnt vmcnt(15)
	v_cvt_pk_f32_fp8_e32 v[140:141], v68
	v_cvt_pk_f32_fp8_sdwa v[142:143], v68 src0_sel:WORD_1
	v_cvt_pk_f32_fp8_e32 v[144:145], v69
	v_cvt_pk_f32_fp8_sdwa v[146:147], v69 src0_sel:WORD_1
	v_pk_mul_f32 v[148:149], v[140:141], v[104:105]
	v_pk_mul_f32 v[150:151], v[142:143], v[106:107]
	v_pk_fma_f32 v[148:149], v[144:145], v[108:109], v[148:149]
	v_pk_fma_f32 v[150:151], v[146:147], v[110:111], v[150:151]
	v_cvt_pk_f32_fp8_e32 v[140:141], v70
	v_cvt_pk_f32_fp8_sdwa v[142:143], v70 src0_sel:WORD_1
	v_cvt_pk_f32_fp8_e32 v[144:145], v71
	v_cvt_pk_f32_fp8_sdwa v[146:147], v71 src0_sel:WORD_1
	v_pk_fma_f32 v[148:149], v[140:141], v[112:113], v[148:149]
	v_pk_fma_f32 v[150:151], v[142:143], v[114:115], v[150:151]
	v_pk_fma_f32 v[148:149], v[144:145], v[116:117], v[148:149]
	v_pk_fma_f32 v[150:151], v[146:147], v[118:119], v[150:151]
	v_pk_add_f32 v[148:149], v[148:149], v[150:151]
	s_nop 0
	v_add_f32_e32 v173, v148, v149
	v_lshl_add_u32 v4, v103, 7, v0
	global_load_dwordx4 v[68:71], v4, s[40:41]
	v_cndmask_b32_e64 v152, v156, v157, s[34:35]
	v_cndmask_b32_e64 v174, v157, v156, s[34:35]
	v_cndmask_b32_e64 v153, v158, v159, s[34:35]
	v_cndmask_b32_e64 v175, v159, v158, s[34:35]
	v_cndmask_b32_e64 v154, v160, v161, s[34:35]
	v_cndmask_b32_e64 v176, v161, v160, s[34:35]
	v_cndmask_b32_e64 v155, v162, v163, s[34:35]
	v_cndmask_b32_e64 v177, v163, v162, s[34:35]
	v_add_f32_dpp v156, v174, v152 quad_perm:[1,0,3,2] row_mask:0xf bank_mask:0xf
	v_add_f32_dpp v157, v175, v153 quad_perm:[1,0,3,2] row_mask:0xf bank_mask:0xf
; DI float dots4h(const u32x4 xa, const u32x4 xb, const u32x4 b0, const u32x4 b1, const u32x4 b2, const u32x4 b3, int lane) {
;     const float d0 = dot16p(xa, xb, b0), d1 = dot16p(xa, xb, b1); __builtin_amdgcn_sched_barrier(0);
;     const float d2 = dot16p(xa, xb, b2), d3 = dot16p(xa, xb, b3); __builtin_amdgcn_sched_barrier(0);
;     const bool p1 = lane & 1, p2 = lane & 2;
;     const float b0s = (p1 ? d1 : d0) + __shfl_xor(p1 ? d0 : d1, 1);
;     const float b1s = (p1 ? d3 : d2) + __shfl_xor(p1 ? d2 : d3, 1);
;     float cs = (p2 ? b1s : b0s) + __shfl_xor(p2 ? b0s : b1s, 2);
;     cs += __shfl_xor(cs, 4); cs += __shfl_xor(cs, 8); cs += __shfl_xor(cs, 16); cs += __shfl_xor(cs, 32);
;     return cs;
; DI void phase_peer_u(const Args& a, int layer, int ci) {
;     ...
;             for (int g8 = 0; g8 < 16; ++g8) {
;                 u32x4 nxt[8];
;                 if (g8 < 15) gat_loadhu(U, idA, idB, g8 + 1, lo16, nxt); else gat_loadhu(U, idAn, idBn, 0, lo16, nxt);
;                 const float c0 = dots4h(xa, xb, cur[0], cur[1], cur[2], cur[3], lane);
;                 const float c1 = dots4h(xa, xb, cur[4], cur[5], cur[6], cur[7], lane);
;                 const int q4 = (g8 & 7) * 2;
;                 const float cv = (lane >> 2) == q4 ? c0 : c1;
;                 const bool mine = (lane >> 3) == (g8 & 7);
;                 if (ci == 0) { if (g8 < 8) rA = mine ? cv : rA; else rB = mine ? cv : rB; }
;                 else { if (g8 < 8) rA = mine ? gelu_tanh((cv + pdA) * rstdu) * glA : rA; else rB = mine ? gelu_tanh((cv + pdB) * rstdu) * glB : rB; }
; #pragma unroll
;                 for (int j = 0; j < 8; ++j) cur[j] = nxt[j];
;             }
;             if (ci == 0) { PD[(size_t)m * 128 + lane] = rA; PD[(size_t)m * 128 + 64 + lane] = rB; }
	v_add_f32_dpp v158, v176, v154 quad_perm:[1,0,3,2] row_mask:0xf bank_mask:0xf
	v_add_f32_dpp v159, v177, v155 quad_perm:[1,0,3,2] row_mask:0xf bank_mask:0xf
	v_cndmask_b32_e64 v152, v166, v167, s[34:35]
	v_cndmask_b32_e64 v174, v167, v166, s[34:35]
	v_cndmask_b32_e64 v153, v168, v169, s[34:35]
	v_cndmask_b32_e64 v175, v169, v168, s[34:35]
	v_cndmask_b32_e64 v154, v170, v171, s[34:35]
	v_cndmask_b32_e64 v176, v171, v170, s[34:35]
	v_cndmask_b32_e64 v155, v172, v173, s[34:35]
	v_cndmask_b32_e64 v177, v173, v172, s[34:35]
	v_add_f32_dpp v160, v174, v152 quad_perm:[1,0,3,2] row_mask:0xf bank_mask:0xf
	v_add_f32_dpp v161, v175, v153 quad_perm:[1,0,3,2] row_mask:0xf bank_mask:0xf
	v_add_f32_dpp v162, v176, v154 quad_perm:[1,0,3,2] row_mask:0xf bank_mask:0xf
	v_add_f32_dpp v163, v177, v155 quad_perm:[1,0,3,2] row_mask:0xf bank_mask:0xf
	v_cndmask_b32_e64 v152, v156, v157, s[48:49]
	v_cndmask_b32_e64 v174, v157, v156, s[48:49]
	v_cndmask_b32_e64 v153, v158, v159, s[48:49]
	v_cndmask_b32_e64 v175, v159, v158, s[48:49]
	v_cndmask_b32_e64 v154, v160, v161, s[48:49]
	v_cndmask_b32_e64 v176, v161, v160, s[48:49]
	v_cndmask_b32_e64 v155, v162, v163, s[48:49]
	v_cndmask_b32_e64 v177, v163, v162, s[48:49]
	v_add_f32_dpp v156, v174, v152 quad_perm:[2,3,0,1] row_mask:0xf bank_mask:0xf
	v_add_f32_dpp v157, v175, v153 quad_perm:[2,3,0,1] row_mask:0xf bank_mask:0xf
	v_add_f32_dpp v158, v176, v154 quad_perm:[2,3,0,1] row_mask:0xf bank_mask:0xf
	v_add_f32_dpp v159, v177, v155 quad_perm:[2,3,0,1] row_mask:0xf bank_mask:0xf
	v_mov_b64_e32 v[216:217], v[218:219]
	v_mov_b64_e32 v[218:219], v[220:221]
	v_mov_b64_e32 v[220:221], v[222:223]
	v_mov_b64_e32 v[222:223], v[224:225]
	v_mov_b64_e32 v[224:225], v[226:227]
	v_mov_b64_e32 v[226:227], v[232:233]
	v_mov_b64_e32 v[232:233], v[234:235]
	v_cndmask_b32_e64 v152, v156, v157, s[50:51]
	v_cndmask_b32_e64 v174, v157, v156, s[50:51]
	v_cndmask_b32_e64 v153, v158, v159, s[50:51]
	v_cndmask_b32_e64 v175, v159, v158, s[50:51]
	v_add_f32_dpp v234, v174, v152 row_shl:4 row_mask:0xf bank_mask:0x5
	v_add_f32_dpp v234, v174, v152 row_shr:4 row_mask:0xf bank_mask:0xa
	v_add_f32_dpp v235, v175, v153 row_shl:4 row_mask:0xf bank_mask:0x5
	v_add_f32_dpp v235, v175, v153 row_shr:4 row_mask:0xf bank_mask:0xa
	s_cmp_eq_u32 s47, 7
	s_cbranch_scc0 .Lpu_b0_nost
	s_bfe_u32 s45, s0, 0x40003
	s_lshl_b32 s45, s45, 20
	s_add_u32 s45, s45, s8
	s_lshr_b32 s46, s0, 7
	s_add_u32 s46, s46, s9
	s_lshl_b32 s46, s46, 24
	s_add_u32 s45, s45, s46
	s_add_u32 s45, s45, 0x20000000
	s_add_u32 s42, s98, s45
	s_addc_u32 s43, s99, 0
	global_store_dwordx4 v2, v[216:219], s[42:43]
	global_store_dwordx4 v2, v[220:223], s[42:43] offset:128
	global_store_dwordx4 v2, v[224:227], s[42:43] offset:256
	global_store_dwordx4 v2, v[232:235], s[42:43] offset:384
	v_lshlrev_b32_e32 v104, 16, v120
	v_and_b32_e32 v105, 0xffff0000, v120
	v_lshlrev_b32_e32 v106, 16, v121
	v_and_b32_e32 v107, 0xffff0000, v121
	v_lshlrev_b32_e32 v108, 16, v122
	v_and_b32_e32 v109, 0xffff0000, v122
	v_lshlrev_b32_e32 v110, 16, v123
	v_and_b32_e32 v111, 0xffff0000, v123
	v_lshlrev_b32_e32 v112, 16, v124
	v_and_b32_e32 v113, 0xffff0000, v124
	v_lshlrev_b32_e32 v114, 16, v125
	v_and_b32_e32 v115, 0xffff0000, v125
	v_lshlrev_b32_e32 v116, 16, v126
	v_and_b32_e32 v117, 0xffff0000, v126
	v_lshlrev_b32_e32 v118, 16, v127
	v_and_b32_e32 v119, 0xffff0000, v127
.Lpu_b0_nost:
	s_add_u32 s0, s0, 1
	s_add_u32 s44, s0, 1
	s_min_u32 s44, s44, 0xff
	s_lshr_b32 s46, s44, 7
	s_add_u32 s46, s46, s9
	s_lshl_b32 s46, s46, 21
	s_add_u32 s40, s16, s46
	s_addc_u32 s41, s17, 0
	s_and_b32 s47, s0, 7
	s_cmp_eq_u32 s47, 0
	s_cbranch_scc0 .Lpu_b1_nox
	s_lshr_b32 s19, s0, 3
	s_add_u32 s19, s19, 1
	s_min_u32 s19, s19, 31
	s_and_b32 s45, s19, 15
	s_lshl_b32 s45, s45, 20
	s_add_u32 s45, s45, s8
	s_and_b32 s46, s19, 1
	s_lshl_b32 s46, s46, 12
	s_add_u32 s46, s46, s1
	s_add_u32 s100, s45, 0x6000000
	s_add_u32 s22, s98, s100
	s_addc_u32 s23, s99, 0
	v_lshl_add_u64 v[6:7], s[22:23], 0, v[238:239]
	s_mov_b32 m0, s46
	s_nop 0
	global_load_lds_dwordx4 v[6:7], off
	global_load_lds_dwordx4 v[6:7], off offset:1024
	global_load_lds_dwordx4 v[6:7], off offset:2048
	global_load_lds_dwordx4 v[6:7], off offset:3072
	s_and_b32 s45, s19, 15
	s_lshl_b32 s45, s45, 23
	s_lshl_b32 s46, s8, 3
	s_add_u32 s45, s45, s46
	s_lshr_b32 s46, s19, 4
	s_add_u32 s46, s46, s9
	s_lshl_b32 s46, s46, 8
	s_add_u32 s45, s45, s46
	s_add_u32 s24, s20, s45
	s_addc_u32 s25, s21, 0
	global_load_dwordx4 v[120:123], v236, s[24:25]
	global_load_dwordx4 v[124:127], v236, s[24:25] offset:16
; #define FP8_LO(w) __builtin_amdgcn_cvt_pk_f32_fp8((int)(w), false)
; #define FP8_HI(w) __builtin_amdgcn_cvt_pk_f32_fp8((int)(w), true)
; DI float dot16p(const u32x4 xa, const u32x4 xb, const u32x4 w) {
;     const f32x2 a0 = FP8_LO(w.x), a1 = FP8_HI(w.x), a2 = FP8_LO(w.y), a3 = FP8_HI(w.y), a4 = FP8_LO(w.z), a5 = FP8_HI(w.z), a6 = FP8_LO(w.w), a7 = FP8_HI(w.w);
;     return (bflo(xa.x) * a0.x + bfhi(xa.x) * a0.y + bflo(xa.y) * a1.x + bfhi(xa.y) * a1.y) + (bflo(xa.z) * a2.x + bfhi(xa.z) * a2.y + bflo(xa.w) * a3.x + bfhi(xa.w) * a3.y)
;          + (bflo(xb.x) * a4.x + bfhi(xb.x) * a4.y + bflo(xb.y) * a5.x + bfhi(xb.y) * a5.y) + (bflo(xb.z) * a6.x + bfhi(xb.z) * a6.y + bflo(xb.w) * a7.x + bfhi(xb.w) * a7.y);
; }
; DI void phase_peer_u(const Args& a, int layer, int ci) {
;     ...
;             for (int g8 = 0; g8 < 16; ++g8) {
;                 u32x4 nxt[8];
;                 if (g8 < 15) gat_loadhu(U, idA, idB, g8 + 1, lo16, nxt); else gat_loadhu(U, idAn, idBn, 0, lo16, nxt);
;                 const float c0 = dots4h(xa, xb, cur[0], cur[1], cur[2], cur[3], lane);
;                 const float c1 = dots4h(xa, xb, cur[4], cur[5], cur[6], cur[7], lane);
.Lpu_b1_nox:
	s_waitcnt lgkmcnt(0)
	s_add_u32 s44, s0, 2
	s_min_u32 s44, s44, 0xff
	s_bfe_u32 s45, s44, 0x10003
	s_lshl_b32 s45, s45, 12
	s_and_b32 s46, s44, 7
	s_lshl_b32 s46, s46, 6
	s_add_u32 s45, s45, s46
	v_add_u32_e32 v5, s45, v240
	ds_read_b128 v[88:91], v5
	ds_read_b128 v[92:95], v5 offset:16
	ds_read_b128 v[96:99], v5 offset:32
	ds_read_b128 v[100:103], v5 offset:48
	s_waitcnt vmcnt(15)
	v_cvt_pk_f32_fp8_e32 v[140:141], v8
	v_cvt_pk_f32_fp8_sdwa v[142:143], v8 src0_sel:WORD_1
	v_cvt_pk_f32_fp8_e32 v[144:145], v9
	v_cvt_pk_f32_fp8_sdwa v[146:147], v9 src0_sel:WORD_1
	v_pk_mul_f32 v[148:149], v[140:141], v[104:105]
	v_pk_mul_f32 v[150:151], v[142:143], v[106:107]
	v_pk_fma_f32 v[148:149], v[144:145], v[108:109], v[148:149]
	v_pk_fma_f32 v[150:151], v[146:147], v[110:111], v[150:151]
	v_cvt_pk_f32_fp8_e32 v[140:141], v10
	v_cvt_pk_f32_fp8_sdwa v[142:143], v10 src0_sel:WORD_1
	v_cvt_pk_f32_fp8_e32 v[144:145], v11
	v_cvt_pk_f32_fp8_sdwa v[146:147], v11 src0_sel:WORD_1
	v_pk_fma_f32 v[148:149], v[140:141], v[112:113], v[148:149]
	v_pk_fma_f32 v[150:151], v[142:143], v[114:115], v[150:151]
	v_pk_fma_f32 v[148:149], v[144:145], v[116:117], v[148:149]
	v_pk_fma_f32 v[150:151], v[146:147], v[118:119], v[150:151]
	v_pk_add_f32 v[148:149], v[148:149], v[150:151]
	s_nop 0
	v_add_f32_e32 v156, v148, v149
	v_lshl_add_u32 v3, v72, 7, v0
	global_load_dwordx4 v[8:11], v3, s[40:41]
	s_waitcnt vmcnt(15)
	v_cvt_pk_f32_fp8_e32 v[140:141], v12
	v_cvt_pk_f32_fp8_sdwa v[142:143], v12 src0_sel:WORD_1
	v_cvt_pk_f32_fp8_e32 v[144:145], v13
	v_cvt_pk_f32_fp8_sdwa v[146:147], v13 src0_sel:WORD_1
	v_pk_mul_f32 v[148:149], v[140:141], v[104:105]
	v_pk_mul_f32 v[150:151], v[142:143], v[106:107]
	v_pk_fma_f32 v[148:149], v[144:145], v[108:109], v[148:149]
	v_pk_fma_f32 v[150:151], v[146:147], v[110:111], v[150:151]
	v_cvt_pk_f32_fp8_e32 v[140:141], v14
	v_cvt_pk_f32_fp8_sdwa v[142:143], v14 src0_sel:WORD_1
	v_cvt_pk_f32_fp8_e32 v[144:145], v15
	v_cvt_pk_f32_fp8_sdwa v[146:147], v15 src0_sel:WORD_1
	v_pk_fma_f32 v[148:149], v[140:141], v[112:113], v[148:149]
	v_pk_fma_f32 v[150:151], v[142:143], v[114:115], v[150:151]
	v_pk_fma_f32 v[148:149], v[144:145], v[116:117], v[148:149]
	v_pk_fma_f32 v[150:151], v[146:147], v[118:119], v[150:151]
	v_pk_add_f32 v[148:149], v[148:149], v[150:151]
	s_nop 0
	v_add_f32_e32 v157, v148, v149
	v_lshl_add_u32 v4, v73, 7, v0
	global_load_dwordx4 v[12:15], v4, s[40:41]
	s_waitcnt vmcnt(15)
	v_cvt_pk_f32_fp8_e32 v[140:141], v16
	v_cvt_pk_f32_fp8_sdwa v[142:143], v16 src0_sel:WORD_1
	v_cvt_pk_f32_fp8_e32 v[144:145], v17
	v_cvt_pk_f32_fp8_sdwa v[146:147], v17 src0_sel:WORD_1
	v_pk_mul_f32 v[148:149], v[140:141], v[104:105]
	v_pk_mul_f32 v[150:151], v[142:143], v[106:107]
	v_pk_fma_f32 v[148:149], v[144:145], v[108:109], v[148:149]
	v_pk_fma_f32 v[150:151], v[146:147], v[110:111], v[150:151]
	v_cvt_pk_f32_fp8_e32 v[140:141], v18
	v_cvt_pk_f32_fp8_sdwa v[142:143], v18 src0_sel:WORD_1
	v_cvt_pk_f32_fp8_e32 v[144:145], v19
	v_cvt_pk_f32_fp8_sdwa v[146:147], v19 src0_sel:WORD_1
	v_pk_fma_f32 v[148:149], v[140:141], v[112:113], v[148:149]
	v_pk_fma_f32 v[150:151], v[142:143], v[114:115], v[150:151]
	v_pk_fma_f32 v[148:149], v[144:145], v[116:117], v[148:149]
	v_pk_fma_f32 v[150:151], v[146:147], v[118:119], v[150:151]
	v_pk_add_f32 v[148:149], v[148:149], v[150:151]
	s_nop 0
	v_add_f32_e32 v158, v148, v149
	v_lshl_add_u32 v3, v74, 7, v0
	global_load_dwordx4 v[16:19], v3, s[40:41]
	s_waitcnt vmcnt(15)
	v_cvt_pk_f32_fp8_e32 v[140:141], v20
	v_cvt_pk_f32_fp8_sdwa v[142:143], v20 src0_sel:WORD_1
	v_cvt_pk_f32_fp8_e32 v[144:145], v21
	v_cvt_pk_f32_fp8_sdwa v[146:147], v21 src0_sel:WORD_1
	v_pk_mul_f32 v[148:149], v[140:141], v[104:105]
	v_pk_mul_f32 v[150:151], v[142:143], v[106:107]
	v_pk_fma_f32 v[148:149], v[144:145], v[108:109], v[148:149]
	v_pk_fma_f32 v[150:151], v[146:147], v[110:111], v[150:151]
	v_cvt_pk_f32_fp8_e32 v[140:141], v22
	v_cvt_pk_f32_fp8_sdwa v[142:143], v22 src0_sel:WORD_1
	v_cvt_pk_f32_fp8_e32 v[144:145], v23
	v_cvt_pk_f32_fp8_sdwa v[146:147], v23 src0_sel:WORD_1
	v_pk_fma_f32 v[148:149], v[140:141], v[112:113], v[148:149]
	v_pk_fma_f32 v[150:151], v[142:143], v[114:115], v[150:151]
	v_pk_fma_f32 v[148:149], v[144:145], v[116:117], v[148:149]
	v_pk_fma_f32 v[150:151], v[146:147], v[118:119], v[150:151]
	v_pk_add_f32 v[148:149], v[148:149], v[150:151]
	s_nop 0
	v_add_f32_e32 v159, v148, v149
	v_lshl_add_u32 v4, v75, 7, v0
	global_load_dwordx4 v[20:23], v4, s[40:41]
	s_waitcnt vmcnt(15)
	v_cvt_pk_f32_fp8_e32 v[140:141], v24
	v_cvt_pk_f32_fp8_sdwa v[142:143], v24 src0_sel:WORD_1
	v_cvt_pk_f32_fp8_e32 v[144:145], v25
	v_cvt_pk_f32_fp8_sdwa v[146:147], v25 src0_sel:WORD_1
	v_pk_mul_f32 v[148:149], v[140:141], v[104:105]
	v_pk_mul_f32 v[150:151], v[142:143], v[106:107]
	v_pk_fma_f32 v[148:149], v[144:145], v[108:109], v[148:149]
	v_pk_fma_f32 v[150:151], v[146:147], v[110:111], v[150:151]
	v_cvt_pk_f32_fp8_e32 v[140:141], v26
	v_cvt_pk_f32_fp8_sdwa v[142:143], v26 src0_sel:WORD_1
	v_cvt_pk_f32_fp8_e32 v[144:145], v27
	v_cvt_pk_f32_fp8_sdwa v[146:147], v27 src0_sel:WORD_1
	v_pk_fma_f32 v[148:149], v[140:141], v[112:113], v[148:149]
	v_pk_fma_f32 v[150:151], v[142:143], v[114:115], v[150:151]
	v_pk_fma_f32 v[148:149], v[144:145], v[116:117], v[148:149]
	v_pk_fma_f32 v[150:151], v[146:147], v[118:119], v[150:151]
	v_pk_add_f32 v[148:149], v[148:149], v[150:151]
	s_nop 0
	v_add_f32_e32 v160, v148, v149
	v_lshl_add_u32 v3, v76, 7, v0
	global_load_dwordx4 v[24:27], v3, s[40:41]
	s_waitcnt vmcnt(15)
; #define FP8_LO(w) __builtin_amdgcn_cvt_pk_f32_fp8((int)(w), false)
; #define FP8_HI(w) __builtin_amdgcn_cvt_pk_f32_fp8((int)(w), true)
; DI float dot16p(const u32x4 xa, const u32x4 xb, const u32x4 w) {
;     const f32x2 a0 = FP8_LO(w.x), a1 = FP8_HI(w.x), a2 = FP8_LO(w.y), a3 = FP8_HI(w.y), a4 = FP8_LO(w.z), a5 = FP8_HI(w.z), a6 = FP8_LO(w.w), a7 = FP8_HI(w.w);
;     return (bflo(xa.x) * a0.x + bfhi(xa.x) * a0.y + bflo(xa.y) * a1.x + bfhi(xa.y) * a1.y) + (bflo(xa.z) * a2.x + bfhi(xa.z) * a2.y + bflo(xa.w) * a3.x + bfhi(xa.w) * a3.y)
;          + (bflo(xb.x) * a4.x + bfhi(xb.x) * a4.y + bflo(xb.y) * a5.x + bfhi(xb.y) * a5.y) + (bflo(xb.z) * a6.x + bfhi(xb.z) * a6.y + bflo(xb.w) * a7.x + bfhi(xb.w) * a7.y);
; }
; DI void phase_peer_u(const Args& a, int layer, int ci) {
;     ...
;                 const float c0 = dots4h(xa, xb, cur[0], cur[1], cur[2], cur[3], lane);
;                 const float c1 = dots4h(xa, xb, cur[4], cur[5], cur[6], cur[7], lane);
	v_cvt_pk_f32_fp8_e32 v[140:141], v28
	v_cvt_pk_f32_fp8_sdwa v[142:143], v28 src0_sel:WORD_1
	v_cvt_pk_f32_fp8_e32 v[144:145], v29
	v_cvt_pk_f32_fp8_sdwa v[146:147], v29 src0_sel:WORD_1
	v_pk_mul_f32 v[148:149], v[140:141], v[104:105]
	v_pk_mul_f32 v[150:151], v[142:143], v[106:107]
	v_pk_fma_f32 v[148:149], v[144:145], v[108:109], v[148:149]
	v_pk_fma_f32 v[150:151], v[146:147], v[110:111], v[150:151]
	v_cvt_pk_f32_fp8_e32 v[140:141], v30
	v_cvt_pk_f32_fp8_sdwa v[142:143], v30 src0_sel:WORD_1
	v_cvt_pk_f32_fp8_e32 v[144:145], v31
	v_cvt_pk_f32_fp8_sdwa v[146:147], v31 src0_sel:WORD_1
	v_pk_fma_f32 v[148:149], v[140:141], v[112:113], v[148:149]
	v_pk_fma_f32 v[150:151], v[142:143], v[114:115], v[150:151]
	v_pk_fma_f32 v[148:149], v[144:145], v[116:117], v[148:149]
	v_pk_fma_f32 v[150:151], v[146:147], v[118:119], v[150:151]
	v_pk_add_f32 v[148:149], v[148:149], v[150:151]
	s_nop 0
	v_add_f32_e32 v161, v148, v149
	v_lshl_add_u32 v4, v77, 7, v0
	global_load_dwordx4 v[28:31], v4, s[40:41]
	s_waitcnt vmcnt(15)
	v_cvt_pk_f32_fp8_e32 v[140:141], v32
	v_cvt_pk_f32_fp8_sdwa v[142:143], v32 src0_sel:WORD_1
	v_cvt_pk_f32_fp8_e32 v[144:145], v33
	v_cvt_pk_f32_fp8_sdwa v[146:147], v33 src0_sel:WORD_1
	v_pk_mul_f32 v[148:149], v[140:141], v[104:105]
	v_pk_mul_f32 v[150:151], v[142:143], v[106:107]
	v_pk_fma_f32 v[148:149], v[144:145], v[108:109], v[148:149]
	v_pk_fma_f32 v[150:151], v[146:147], v[110:111], v[150:151]
	v_cvt_pk_f32_fp8_e32 v[140:141], v34
	v_cvt_pk_f32_fp8_sdwa v[142:143], v34 src0_sel:WORD_1
	v_cvt_pk_f32_fp8_e32 v[144:145], v35
	v_cvt_pk_f32_fp8_sdwa v[146:147], v35 src0_sel:WORD_1
	v_pk_fma_f32 v[148:149], v[140:141], v[112:113], v[148:149]
	v_pk_fma_f32 v[150:151], v[142:143], v[114:115], v[150:151]
	v_pk_fma_f32 v[148:149], v[144:145], v[116:117], v[148:149]
	v_pk_fma_f32 v[150:151], v[146:147], v[118:119], v[150:151]
	v_pk_add_f32 v[148:149], v[148:149], v[150:151]
	s_nop 0
	v_add_f32_e32 v162, v148, v149
	v_lshl_add_u32 v3, v78, 7, v0
	global_load_dwordx4 v[32:35], v3, s[40:41]
	s_waitcnt vmcnt(15)
	v_cvt_pk_f32_fp8_e32 v[140:141], v36
	v_cvt_pk_f32_fp8_sdwa v[142:143], v36 src0_sel:WORD_1
	v_cvt_pk_f32_fp8_e32 v[144:145], v37
	v_cvt_pk_f32_fp8_sdwa v[146:147], v37 src0_sel:WORD_1
	v_pk_mul_f32 v[148:149], v[140:141], v[104:105]
	v_pk_mul_f32 v[150:151], v[142:143], v[106:107]
	v_pk_fma_f32 v[148:149], v[144:145], v[108:109], v[148:149]
	v_pk_fma_f32 v[150:151], v[146:147], v[110:111], v[150:151]
	v_cvt_pk_f32_fp8_e32 v[140:141], v38
	v_cvt_pk_f32_fp8_sdwa v[142:143], v38 src0_sel:WORD_1
	v_cvt_pk_f32_fp8_e32 v[144:145], v39
	v_cvt_pk_f32_fp8_sdwa v[146:147], v39 src0_sel:WORD_1
	v_pk_fma_f32 v[148:149], v[140:141], v[112:113], v[148:149]
	v_pk_fma_f32 v[150:151], v[142:143], v[114:115], v[150:151]
	v_pk_fma_f32 v[148:149], v[144:145], v[116:117], v[148:149]
	v_pk_fma_f32 v[150:151], v[146:147], v[118:119], v[150:151]
	v_pk_add_f32 v[148:149], v[148:149], v[150:151]
	s_nop 0
	v_add_f32_e32 v163, v148, v149
	v_lshl_add_u32 v4, v79, 7, v0
	global_load_dwordx4 v[36:39], v4, s[40:41]
	s_waitcnt vmcnt(15)
	v_cvt_pk_f32_fp8_e32 v[140:141], v40
	v_cvt_pk_f32_fp8_sdwa v[142:143], v40 src0_sel:WORD_1
	v_cvt_pk_f32_fp8_e32 v[144:145], v41
	v_cvt_pk_f32_fp8_sdwa v[146:147], v41 src0_sel:WORD_1
	v_pk_mul_f32 v[148:149], v[140:141], v[104:105]
	v_pk_mul_f32 v[150:151], v[142:143], v[106:107]
	v_pk_fma_f32 v[148:149], v[144:145], v[108:109], v[148:149]
	v_pk_fma_f32 v[150:151], v[146:147], v[110:111], v[150:151]
	v_cvt_pk_f32_fp8_e32 v[140:141], v42
	v_cvt_pk_f32_fp8_sdwa v[142:143], v42 src0_sel:WORD_1
	v_cvt_pk_f32_fp8_e32 v[144:145], v43
	v_cvt_pk_f32_fp8_sdwa v[146:147], v43 src0_sel:WORD_1
	v_pk_fma_f32 v[148:149], v[140:141], v[112:113], v[148:149]
	v_pk_fma_f32 v[150:151], v[142:143], v[114:115], v[150:151]
	v_pk_fma_f32 v[148:149], v[144:145], v[116:117], v[148:149]
	v_pk_fma_f32 v[150:151], v[146:147], v[118:119], v[150:151]
	v_pk_add_f32 v[148:149], v[148:149], v[150:151]
	s_nop 0
	v_add_f32_e32 v166, v148, v149
	v_lshl_add_u32 v3, v80, 7, v0
	global_load_dwordx4 v[40:43], v3, s[40:41]
	s_waitcnt vmcnt(15)
	v_cvt_pk_f32_fp8_e32 v[140:141], v44
	v_cvt_pk_f32_fp8_sdwa v[142:143], v44 src0_sel:WORD_1
	v_cvt_pk_f32_fp8_e32 v[144:145], v45
	v_cvt_pk_f32_fp8_sdwa v[146:147], v45 src0_sel:WORD_1
	v_pk_mul_f32 v[148:149], v[140:141], v[104:105]
	v_pk_mul_f32 v[150:151], v[142:143], v[106:107]
	v_pk_fma_f32 v[148:149], v[144:145], v[108:109], v[148:149]
	v_pk_fma_f32 v[150:151], v[146:147], v[110:111], v[150:151]
	v_cvt_pk_f32_fp8_e32 v[140:141], v46
	v_cvt_pk_f32_fp8_sdwa v[142:143], v46 src0_sel:WORD_1
	v_cvt_pk_f32_fp8_e32 v[144:145], v47
	v_cvt_pk_f32_fp8_sdwa v[146:147], v47 src0_sel:WORD_1
	v_pk_fma_f32 v[148:149], v[140:141], v[112:113], v[148:149]
	v_pk_fma_f32 v[150:151], v[142:143], v[114:115], v[150:151]
	v_pk_fma_f32 v[148:149], v[144:145], v[116:117], v[148:149]
	v_pk_fma_f32 v[150:151], v[146:147], v[118:119], v[150:151]
	v_pk_add_f32 v[148:149], v[148:149], v[150:151]
	s_nop 0
	v_add_f32_e32 v167, v148, v149
	v_lshl_add_u32 v4, v81, 7, v0
	global_load_dwordx4 v[44:47], v4, s[40:41]
	s_waitcnt vmcnt(15)
	v_cvt_pk_f32_fp8_e32 v[140:141], v48
	v_cvt_pk_f32_fp8_sdwa v[142:143], v48 src0_sel:WORD_1
	v_cvt_pk_f32_fp8_e32 v[144:145], v49
	v_cvt_pk_f32_fp8_sdwa v[146:147], v49 src0_sel:WORD_1
	v_pk_mul_f32 v[148:149], v[140:141], v[104:105]
	v_pk_mul_f32 v[150:151], v[142:143], v[106:107]
	v_pk_fma_f32 v[148:149], v[144:145], v[108:109], v[148:149]
	v_pk_fma_f32 v[150:151], v[146:147], v[110:111], v[150:151]
	v_cvt_pk_f32_fp8_e32 v[140:141], v50
	v_cvt_pk_f32_fp8_sdwa v[142:143], v50 src0_sel:WORD_1
	v_cvt_pk_f32_fp8_e32 v[144:145], v51
	v_cvt_pk_f32_fp8_sdwa v[146:147], v51 src0_sel:WORD_1
	v_pk_fma_f32 v[148:149], v[140:141], v[112:113], v[148:149]
	v_pk_fma_f32 v[150:151], v[142:143], v[114:115], v[150:151]
	v_pk_fma_f32 v[148:149], v[144:145], v[116:117], v[148:149]
	v_pk_fma_f32 v[150:151], v[146:147], v[118:119], v[150:151]
	v_pk_add_f32 v[148:149], v[148:149], v[150:151]
	s_nop 0
	v_add_f32_e32 v168, v148, v149
	v_lshl_add_u32 v3, v82, 7, v0
	global_load_dwordx4 v[48:51], v3, s[40:41]
	s_waitcnt vmcnt(15)
; #define FP8_LO(w) __builtin_amdgcn_cvt_pk_f32_fp8((int)(w), false)
; #define FP8_HI(w) __builtin_amdgcn_cvt_pk_f32_fp8((int)(w), true)
; DI float dot16p(const u32x4 xa, const u32x4 xb, const u32x4 w) {
;     const f32x2 a0 = FP8_LO(w.x), a1 = FP8_HI(w.x), a2 = FP8_LO(w.y), a3 = FP8_HI(w.y), a4 = FP8_LO(w.z), a5 = FP8_HI(w.z), a6 = FP8_LO(w.w), a7 = FP8_HI(w.w);
;     return (bflo(xa.x) * a0.x + bfhi(xa.x) * a0.y + bflo(xa.y) * a1.x + bfhi(xa.y) * a1.y) + (bflo(xa.z) * a2.x + bfhi(xa.z) * a2.y + bflo(xa.w) * a3.x + bfhi(xa.w) * a3.y)
;          + (bflo(xb.x) * a4.x + bfhi(xb.x) * a4.y + bflo(xb.y) * a5.x + bfhi(xb.y) * a5.y) + (bflo(xb.z) * a6.x + bfhi(xb.z) * a6.y + bflo(xb.w) * a7.x + bfhi(xb.w) * a7.y);
; }
; DI void phase_peer_u(const Args& a, int layer, int ci) {
;     ...
;                 const float c0 = dots4h(xa, xb, cur[0], cur[1], cur[2], cur[3], lane);
;                 const float c1 = dots4h(xa, xb, cur[4], cur[5], cur[6], cur[7], lane);
	v_cvt_pk_f32_fp8_e32 v[140:141], v52
	v_cvt_pk_f32_fp8_sdwa v[142:143], v52 src0_sel:WORD_1
	v_cvt_pk_f32_fp8_e32 v[144:145], v53
	v_cvt_pk_f32_fp8_sdwa v[146:147], v53 src0_sel:WORD_1
	v_pk_mul_f32 v[148:149], v[140:141], v[104:105]
	v_pk_mul_f32 v[150:151], v[142:143], v[106:107]
	v_pk_fma_f32 v[148:149], v[144:145], v[108:109], v[148:149]
	v_pk_fma_f32 v[150:151], v[146:147], v[110:111], v[150:151]
	v_cvt_pk_f32_fp8_e32 v[140:141], v54
	v_cvt_pk_f32_fp8_sdwa v[142:143], v54 src0_sel:WORD_1
	v_cvt_pk_f32_fp8_e32 v[144:145], v55
	v_cvt_pk_f32_fp8_sdwa v[146:147], v55 src0_sel:WORD_1
	v_pk_fma_f32 v[148:149], v[140:141], v[112:113], v[148:149]
	v_pk_fma_f32 v[150:151], v[142:143], v[114:115], v[150:151]
	v_pk_fma_f32 v[148:149], v[144:145], v[116:117], v[148:149]
	v_pk_fma_f32 v[150:151], v[146:147], v[118:119], v[150:151]
	v_pk_add_f32 v[148:149], v[148:149], v[150:151]
	s_nop 0
	v_add_f32_e32 v169, v148, v149
	v_lshl_add_u32 v4, v83, 7, v0
	global_load_dwordx4 v[52:55], v4, s[40:41]
	s_waitcnt vmcnt(15)
	v_cvt_pk_f32_fp8_e32 v[140:141], v56
	v_cvt_pk_f32_fp8_sdwa v[142:143], v56 src0_sel:WORD_1
	v_cvt_pk_f32_fp8_e32 v[144:145], v57
	v_cvt_pk_f32_fp8_sdwa v[146:147], v57 src0_sel:WORD_1
	v_pk_mul_f32 v[148:149], v[140:141], v[104:105]
	v_pk_mul_f32 v[150:151], v[142:143], v[106:107]
	v_pk_fma_f32 v[148:149], v[144:145], v[108:109], v[148:149]
	v_pk_fma_f32 v[150:151], v[146:147], v[110:111], v[150:151]
	v_cvt_pk_f32_fp8_e32 v[140:141], v58
	v_cvt_pk_f32_fp8_sdwa v[142:143], v58 src0_sel:WORD_1
	v_cvt_pk_f32_fp8_e32 v[144:145], v59
	v_cvt_pk_f32_fp8_sdwa v[146:147], v59 src0_sel:WORD_1
	v_pk_fma_f32 v[148:149], v[140:141], v[112:113], v[148:149]
	v_pk_fma_f32 v[150:151], v[142:143], v[114:115], v[150:151]
	v_pk_fma_f32 v[148:149], v[144:145], v[116:117], v[148:149]
	v_pk_fma_f32 v[150:151], v[146:147], v[118:119], v[150:151]
	v_pk_add_f32 v[148:149], v[148:149], v[150:151]
	s_nop 0
	v_add_f32_e32 v170, v148, v149
	v_lshl_add_u32 v3, v84, 7, v0
	global_load_dwordx4 v[56:59], v3, s[40:41]
	s_waitcnt vmcnt(15)
	v_cvt_pk_f32_fp8_e32 v[140:141], v60
	v_cvt_pk_f32_fp8_sdwa v[142:143], v60 src0_sel:WORD_1
	v_cvt_pk_f32_fp8_e32 v[144:145], v61
	v_cvt_pk_f32_fp8_sdwa v[146:147], v61 src0_sel:WORD_1
	v_pk_mul_f32 v[148:149], v[140:141], v[104:105]
	v_pk_mul_f32 v[150:151], v[142:143], v[106:107]
	v_pk_fma_f32 v[148:149], v[144:145], v[108:109], v[148:149]
	v_pk_fma_f32 v[150:151], v[146:147], v[110:111], v[150:151]
	v_cvt_pk_f32_fp8_e32 v[140:141], v62
	v_cvt_pk_f32_fp8_sdwa v[142:143], v62 src0_sel:WORD_1
	v_cvt_pk_f32_fp8_e32 v[144:145], v63
	v_cvt_pk_f32_fp8_sdwa v[146:147], v63 src0_sel:WORD_1
	v_pk_fma_f32 v[148:149], v[140:141], v[112:113], v[148:149]
	v_pk_fma_f32 v[150:151], v[142:143], v[114:115], v[150:151]
	v_pk_fma_f32 v[148:149], v[144:145], v[116:117], v[148:149]
	v_pk_fma_f32 v[150:151], v[146:147], v[118:119], v[150:151]
	v_pk_add_f32 v[148:149], v[148:149], v[150:151]
	s_nop 0
	v_add_f32_e32 v171, v148, v149
	v_lshl_add_u32 v4, v85, 7, v0
	global_load_dwordx4 v[60:63], v4, s[40:41]
	s_waitcnt vmcnt(15)
	v_cvt_pk_f32_fp8_e32 v[140:141], v64
	v_cvt_pk_f32_fp8_sdwa v[142:143], v64 src0_sel:WORD_1
	v_cvt_pk_f32_fp8_e32 v[144:145], v65
	v_cvt_pk_f32_fp8_sdwa v[146:147], v65 src0_sel:WORD_1
	v_pk_mul_f32 v[148:149], v[140:141], v[104:105]
	v_pk_mul_f32 v[150:151], v[142:143], v[106:107]
	v_pk_fma_f32 v[148:149], v[144:145], v[108:109], v[148:149]
	v_pk_fma_f32 v[150:151], v[146:147], v[110:111], v[150:151]
	v_cvt_pk_f32_fp8_e32 v[140:141], v66
	v_cvt_pk_f32_fp8_sdwa v[142:143], v66 src0_sel:WORD_1
	v_cvt_pk_f32_fp8_e32 v[144:145], v67
	v_cvt_pk_f32_fp8_sdwa v[146:147], v67 src0_sel:WORD_1
	v_pk_fma_f32 v[148:149], v[140:141], v[112:113], v[148:149]
	v_pk_fma_f32 v[150:151], v[142:143], v[114:115], v[150:151]
	v_pk_fma_f32 v[148:149], v[144:145], v[116:117], v[148:149]
	v_pk_fma_f32 v[150:151], v[146:147], v[118:119], v[150:151]
	v_pk_add_f32 v[148:149], v[148:149], v[150:151]
	s_nop 0
	v_add_f32_e32 v172, v148, v149
	v_lshl_add_u32 v3, v86, 7, v0
	global_load_dwordx4 v[64:67], v3, s[40:41]
	s_waitcnt vmcnt(15)
; DI float dots4h(const u32x4 xa, const u32x4 xb, const u32x4 b0, const u32x4 b1, const u32x4 b2, const u32x4 b3, int lane) {
;     const float d0 = dot16p(xa, xb, b0), d1 = dot16p(xa, xb, b1); __builtin_amdgcn_sched_barrier(0);
;     const float d2 = dot16p(xa, xb, b2), d3 = dot16p(xa, xb, b3); __builtin_amdgcn_sched_barrier(0);
;     const bool p1 = lane & 1, p2 = lane & 2;
;     const float b0s = (p1 ? d1 : d0) + __shfl_xor(p1 ? d0 : d1, 1);
;     const float b1s = (p1 ? d3 : d2) + __shfl_xor(p1 ? d2 : d3, 1);
;     float cs = (p2 ? b1s : b0s) + __shfl_xor(p2 ? b0s : b1s, 2);
;     cs += __shfl_xor(cs, 4); cs += __shfl_xor(cs, 8); cs += __shfl_xor(cs, 16); cs += __shfl_xor(cs, 32);
;     return cs;
; DI void phase_peer_u(const Args& a, int layer, int ci) {
;     ...
;             for (int g8 = 0; g8 < 16; ++g8) {
;                 u32x4 nxt[8];
;                 if (g8 < 15) gat_loadhu(U, idA, idB, g8 + 1, lo16, nxt); else gat_loadhu(U, idAn, idBn, 0, lo16, nxt);
;                 const float c0 = dots4h(xa, xb, cur[0], cur[1], cur[2], cur[3], lane);
;                 const float c1 = dots4h(xa, xb, cur[4], cur[5], cur[6], cur[7], lane);
;                 const int q4 = (g8 & 7) * 2;
;                 const float cv = (lane >> 2) == q4 ? c0 : c1;
;                 const bool mine = (lane >> 3) == (g8 & 7);
;                 if (ci == 0) { if (g8 < 8) rA = mine ? cv : rA; else rB = mine ? cv : rB; }
;                 else { if (g8 < 8) rA = mine ? gelu_tanh((cv + pdA) * rstdu) * glA : rA; else rB = mine ? gelu_tanh((cv + pdB) * rstdu) * glB : rB; }
; #pragma unroll
;                 for (int j = 0; j < 8; ++j) cur[j] = nxt[j];
;             }
;             if (ci == 0) { PD[(size_t)m * 128 + lane] = rA; PD[(size_t)m * 128 + 64 + lane] = rB; }
	v_cvt_pk_f32_fp8_e32 v[140:141], v68
	v_cvt_pk_f32_fp8_sdwa v[142:143], v68 src0_sel:WORD_1
	v_cvt_pk_f32_fp8_e32 v[144:145], v69
	v_cvt_pk_f32_fp8_sdwa v[146:147], v69 src0_sel:WORD_1
	v_pk_mul_f32 v[148:149], v[140:141], v[104:105]
	v_pk_mul_f32 v[150:151], v[142:143], v[106:107]
	v_pk_fma_f32 v[148:149], v[144:145], v[108:109], v[148:149]
	v_pk_fma_f32 v[150:151], v[146:147], v[110:111], v[150:151]
	v_cvt_pk_f32_fp8_e32 v[140:141], v70
	v_cvt_pk_f32_fp8_sdwa v[142:143], v70 src0_sel:WORD_1
	v_cvt_pk_f32_fp8_e32 v[144:145], v71
	v_cvt_pk_f32_fp8_sdwa v[146:147], v71 src0_sel:WORD_1
	v_pk_fma_f32 v[148:149], v[140:141], v[112:113], v[148:149]
	v_pk_fma_f32 v[150:151], v[142:143], v[114:115], v[150:151]
	v_pk_fma_f32 v[148:149], v[144:145], v[116:117], v[148:149]
	v_pk_fma_f32 v[150:151], v[146:147], v[118:119], v[150:151]
	v_pk_add_f32 v[148:149], v[148:149], v[150:151]
	s_nop 0
	v_add_f32_e32 v173, v148, v149
	v_lshl_add_u32 v4, v87, 7, v0
	global_load_dwordx4 v[68:71], v4, s[40:41]
	v_cndmask_b32_e64 v152, v156, v157, s[34:35]
	v_cndmask_b32_e64 v174, v157, v156, s[34:35]
	v_cndmask_b32_e64 v153, v158, v159, s[34:35]
	v_cndmask_b32_e64 v175, v159, v158, s[34:35]
	v_cndmask_b32_e64 v154, v160, v161, s[34:35]
	v_cndmask_b32_e64 v176, v161, v160, s[34:35]
	v_cndmask_b32_e64 v155, v162, v163, s[34:35]
	v_cndmask_b32_e64 v177, v163, v162, s[34:35]
	v_add_f32_dpp v156, v174, v152 quad_perm:[1,0,3,2] row_mask:0xf bank_mask:0xf
	v_add_f32_dpp v157, v175, v153 quad_perm:[1,0,3,2] row_mask:0xf bank_mask:0xf
	v_add_f32_dpp v158, v176, v154 quad_perm:[1,0,3,2] row_mask:0xf bank_mask:0xf
	v_add_f32_dpp v159, v177, v155 quad_perm:[1,0,3,2] row_mask:0xf bank_mask:0xf
	v_cndmask_b32_e64 v152, v166, v167, s[34:35]
	v_cndmask_b32_e64 v174, v167, v166, s[34:35]
	v_cndmask_b32_e64 v153, v168, v169, s[34:35]
	v_cndmask_b32_e64 v175, v169, v168, s[34:35]
	v_cndmask_b32_e64 v154, v170, v171, s[34:35]
	v_cndmask_b32_e64 v176, v171, v170, s[34:35]
	v_cndmask_b32_e64 v155, v172, v173, s[34:35]
	v_cndmask_b32_e64 v177, v173, v172, s[34:35]
	v_add_f32_dpp v160, v174, v152 quad_perm:[1,0,3,2] row_mask:0xf bank_mask:0xf
	v_add_f32_dpp v161, v175, v153 quad_perm:[1,0,3,2] row_mask:0xf bank_mask:0xf
	v_add_f32_dpp v162, v176, v154 quad_perm:[1,0,3,2] row_mask:0xf bank_mask:0xf
	v_add_f32_dpp v163, v177, v155 quad_perm:[1,0,3,2] row_mask:0xf bank_mask:0xf
	v_cndmask_b32_e64 v152, v156, v157, s[48:49]
	v_cndmask_b32_e64 v174, v157, v156, s[48:49]
	v_cndmask_b32_e64 v153, v158, v159, s[48:49]
	v_cndmask_b32_e64 v175, v159, v158, s[48:49]
	v_cndmask_b32_e64 v154, v160, v161, s[48:49]
	v_cndmask_b32_e64 v176, v161, v160, s[48:49]
	v_cndmask_b32_e64 v155, v162, v163, s[48:49]
	v_cndmask_b32_e64 v177, v163, v162, s[48:49]
	v_add_f32_dpp v156, v174, v152 quad_perm:[2,3,0,1] row_mask:0xf bank_mask:0xf
	v_add_f32_dpp v157, v175, v153 quad_perm:[2,3,0,1] row_mask:0xf bank_mask:0xf
	v_add_f32_dpp v158, v176, v154 quad_perm:[2,3,0,1] row_mask:0xf bank_mask:0xf
	v_add_f32_dpp v159, v177, v155 quad_perm:[2,3,0,1] row_mask:0xf bank_mask:0xf
	v_mov_b64_e32 v[216:217], v[218:219]
	v_mov_b64_e32 v[218:219], v[220:221]
	v_mov_b64_e32 v[220:221], v[222:223]
	v_mov_b64_e32 v[222:223], v[224:225]
	v_mov_b64_e32 v[224:225], v[226:227]
	v_mov_b64_e32 v[226:227], v[232:233]
	v_mov_b64_e32 v[232:233], v[234:235]
	v_cndmask_b32_e64 v152, v156, v157, s[50:51]
	v_cndmask_b32_e64 v174, v157, v156, s[50:51]
	v_cndmask_b32_e64 v153, v158, v159, s[50:51]
	v_cndmask_b32_e64 v175, v159, v158, s[50:51]
	v_add_f32_dpp v234, v174, v152 row_shl:4 row_mask:0xf bank_mask:0x5
	v_add_f32_dpp v234, v174, v152 row_shr:4 row_mask:0xf bank_mask:0xa
	v_add_f32_dpp v235, v175, v153 row_shl:4 row_mask:0xf bank_mask:0x5
	v_add_f32_dpp v235, v175, v153 row_shr:4 row_mask:0xf bank_mask:0xa
	s_cmp_eq_u32 s47, 7
	s_cbranch_scc0 .Lpu_b1_nost
	s_bfe_u32 s45, s0, 0x40003
	s_lshl_b32 s45, s45, 20
	s_add_u32 s45, s45, s8
	s_lshr_b32 s46, s0, 7
	s_add_u32 s46, s46, s9
	s_lshl_b32 s46, s46, 24
	s_add_u32 s45, s45, s46
	s_add_u32 s45, s45, 0x20000000
	s_add_u32 s42, s98, s45
	s_addc_u32 s43, s99, 0
	global_store_dwordx4 v2, v[216:219], s[42:43]
	global_store_dwordx4 v2, v[220:223], s[42:43] offset:128
	global_store_dwordx4 v2, v[224:227], s[42:43] offset:256
	global_store_dwordx4 v2, v[232:235], s[42:43] offset:384
	v_lshlrev_b32_e32 v104, 16, v120
	v_and_b32_e32 v105, 0xffff0000, v120
	v_lshlrev_b32_e32 v106, 16, v121
	v_and_b32_e32 v107, 0xffff0000, v121
	v_lshlrev_b32_e32 v108, 16, v122
	v_and_b32_e32 v109, 0xffff0000, v122
	v_lshlrev_b32_e32 v110, 16, v123
	v_and_b32_e32 v111, 0xffff0000, v123
	v_lshlrev_b32_e32 v112, 16, v124
	v_and_b32_e32 v113, 0xffff0000, v124
	v_lshlrev_b32_e32 v114, 16, v125
	v_and_b32_e32 v115, 0xffff0000, v125
	v_lshlrev_b32_e32 v116, 16, v126
	v_and_b32_e32 v117, 0xffff0000, v126
	v_lshlrev_b32_e32 v118, 16, v127
	v_and_b32_e32 v119, 0xffff0000, v127
